# attention: softmax scale folded into Q before its bf16 rounding (QKV epilogue), fixed-bound subtraction dropped (shift-invariant, exponent bounded by qk-rmsnorm), 32 VALU FMAs per KV tile removed; 3-d
# baseline (speedup 1.0000x reference)
; #define LAS __attribute__((address_space(3)))
; __device__ __forceinline__ unsigned xb_ld(unsigned* p)              { return __hip_atomic_load(p, __ATOMIC_RELAXED, __HIP_MEMORY_SCOPE_AGENT); }
; __device__ __forceinline__ unsigned xb_add(unsigned* p, unsigned v) { return __hip_atomic_fetch_add(p, v, __ATOMIC_RELAXED, __HIP_MEMORY_SCOPE_AGENT); }
; __device__ __forceinline__ unsigned xb_xcc_id() { return (unsigned)__builtin_amdgcn_s_getreg((3 << 11) | 20) & 0xFu; }
; __device__ __forceinline__ XcdBarrier xcd_barrier_post(unsigned* bar, volatile LAS unsigned* st, int tid) {
;     XcdBarrier b; b.bar = bar; b.x = xb_xcc_id(); b.st = st;
;     if (tid == 0) (void)xb_add(&bar[XB_XCNT(b.x)], 1u);
;     return b;
; }
; __device__ __forceinline__ void xcd_barrier_complete(unsigned* bar, unsigned x, unsigned& nloc, unsigned& nx) {
;     const unsigned G = gridDim.x * gridDim.y * gridDim.z;
;     unsigned sum, cnt, mine, sp = 0u;
;     for (;;) {
;         sum = 0u; cnt = 0u; mine = 0u;
; #pragma unroll
;         for (unsigned j = 0; j < 16; ++j) { const unsigned c = xb_ld(&bar[XB_XCNT(j)]); sum += c; cnt += (c > 0u) ? 1u : 0u; mine = (j == x) ? c : mine; }
;         if (sum == G) break;
;         __builtin_amdgcn_s_sleep(1);
;         if ((++sp & 255u) == 0u) { if (xb_ld(&bar[XB_TMO])) break; if (sp > XB_SPIN_CAP) { atomicAdd(&bar[XB_TMO], 1u); break; } }
;     }
;     nloc = mine > 0u ? mine : 1u; nx = cnt > 0u ? cnt : 1u;
.LBB0_154:
	s_cmp_lt_i32 s80, 0
	s_cselect_b64 s[6:7], -1, 0
	s_add_u32 s96, s0, 0xe0200
	s_addc_u32 s97, s1, 0
	s_add_u32 s90, s0, 0xe0400
	s_addc_u32 s91, s1, 0
	s_add_u32 s92, s0, 0xe0500
	s_addc_u32 s93, s1, 0
	s_add_u32 s86, s0, 0xe0600
	s_mul_i32 s4, s83, s82
	v_lshrrev_b32_e32 v1, 20, v0
	v_lshrrev_b32_e32 v0, 10, v0
	s_addc_u32 s87, s1, 0
	v_writelane_b32 v254, s6, 3
	v_or_b32_e32 v0, v0, v1
	s_movk_i32 s5, 0x3ff
	s_mul_i32 s83, s4, s17
	s_add_u32 s4, s0, 0xe0700
	v_writelane_b32 v254, s7, 4
	v_and_or_b32 v0, v0, s5, v215
	s_addc_u32 s5, s1, 0
	v_writelane_b32 v254, s4, 5
	s_mov_b32 s9, 0
	v_mov_b32_e32 v213, 0
	v_writelane_b32 v254, s5, 6
	s_add_u32 s4, s0, 0xe0800
	s_addc_u32 s5, s1, 0
	v_writelane_b32 v254, s4, 7
	v_mbcnt_lo_u32_b32 v1, -1, 0
	s_movk_i32 s75, 0x4000
	v_writelane_b32 v254, s5, 8
	s_add_u32 s4, s0, 0xe0900
	s_addc_u32 s5, s1, 0
	v_writelane_b32 v254, s4, 9
	s_movk_i32 s54, 0x6000
	s_mov_b32 s55, 0xc000
	v_writelane_b32 v254, s5, 10
	s_add_u32 s4, s0, 0xe0a00
	s_addc_u32 s5, s1, 0
	v_writelane_b32 v254, s4, 11
	s_mov_b32 s27, 0x800000
	v_mov_b32_e32 v247, 1
	v_writelane_b32 v254, s5, 12
	s_add_u32 s4, s0, 0xe0b00
	s_addc_u32 s5, s1, 0
	v_writelane_b32 v254, s4, 13
	v_mbcnt_hi_u32_b32 v246, -1, v1
	v_mov_b32_e32 v214, 0x358637bd
	v_writelane_b32 v254, s5, 14
	s_add_u32 s4, s0, 0xe0c00
	s_addc_u32 s5, s1, 0
	v_writelane_b32 v254, s4, 15
	v_mov_b64_e32 v[252:253], 0x100
	s_mov_b32 s85, 0x5040100
	v_writelane_b32 v254, s5, 16
	s_add_u32 s4, s0, 0xe0d00
	s_addc_u32 s5, s1, 0
	v_writelane_b32 v254, s4, 17
	s_mov_b64 s[10:11], 0x80
	s_mov_b32 s26, 1.0
	v_writelane_b32 v254, s5, 18
	s_add_u32 s4, s0, 0xe0e00
	s_addc_u32 s5, s1, 0
	v_writelane_b32 v254, s4, 19
	s_mov_b64 s[28:29], 0x20000
	s_nop 0
	v_writelane_b32 v254, s5, 20
	s_add_u32 s4, s0, 0xe0f00
	s_addc_u32 s5, s1, 0
	v_writelane_b32 v254, s4, 21
	s_nop 1
	v_writelane_b32 v254, s5, 22
	s_add_u32 s4, s0, 0xe1000
	s_addc_u32 s5, s1, 0
	v_writelane_b32 v254, s4, 23
	s_nop 1
	v_writelane_b32 v254, s5, 24
	s_add_u32 s4, s0, 0xe1100
	s_addc_u32 s5, s1, 0
	v_writelane_b32 v254, s4, 25
	s_nop 1
	v_writelane_b32 v254, s5, 26
	s_add_u32 s4, s0, 0xe1200
	s_addc_u32 s5, s1, 0
	v_writelane_b32 v254, s4, 27
	s_nop 1
	v_writelane_b32 v254, s5, 28
	s_add_u32 s4, s0, 0xe1300
	s_addc_u32 s5, s1, 0
	v_writelane_b32 v254, s4, 29
	s_cmp_eq_u32 s16, 15
	s_nop 0
	v_writelane_b32 v254, s5, 30
	s_cselect_b64 s[4:5], -1, 0
	v_writelane_b32 v254, s4, 31
	s_cmp_eq_u32 s16, 14
	s_nop 0
	v_writelane_b32 v254, s5, 32
	s_cselect_b64 s[4:5], -1, 0
	v_writelane_b32 v254, s4, 33
	s_cmp_eq_u32 s16, 13
	s_nop 0
	v_writelane_b32 v254, s5, 34
	s_cselect_b64 s[4:5], -1, 0
	v_writelane_b32 v254, s4, 35
	s_cmp_eq_u32 s16, 12
	s_nop 0
	v_writelane_b32 v254, s5, 36
	s_cselect_b64 s[4:5], -1, 0
	v_writelane_b32 v254, s4, 37
	s_cmp_eq_u32 s16, 11
	s_nop 0
	v_writelane_b32 v254, s5, 38
	s_cselect_b64 s[4:5], -1, 0
	v_writelane_b32 v254, s4, 39
	s_cmp_eq_u32 s16, 10
	s_nop 0
	v_writelane_b32 v254, s5, 40
	s_cselect_b64 s[4:5], -1, 0
	v_writelane_b32 v254, s4, 41
	s_cmp_eq_u32 s16, 9
	s_nop 0
	v_writelane_b32 v254, s5, 42
	s_cselect_b64 s[4:5], -1, 0
	v_writelane_b32 v254, s4, 43
	s_cmp_eq_u32 s16, 8
	s_nop 0
	v_writelane_b32 v254, s5, 44
	s_cselect_b64 s[4:5], -1, 0
	v_writelane_b32 v254, s4, 45
	s_cmp_eq_u32 s16, 7
	s_nop 0
	v_writelane_b32 v254, s5, 46
	s_cselect_b64 s[4:5], -1, 0
	v_writelane_b32 v254, s4, 47
	s_cmp_eq_u32 s16, 6
	s_nop 0
	v_writelane_b32 v254, s5, 48
	s_cselect_b64 s[4:5], -1, 0
	v_writelane_b32 v254, s4, 49
	s_cmp_eq_u32 s16, 5
	s_nop 0
	v_writelane_b32 v254, s5, 50
	s_cselect_b64 s[4:5], -1, 0
	v_writelane_b32 v254, s4, 51
	s_cmp_eq_u32 s16, 4
	s_nop 0
	v_writelane_b32 v254, s5, 52
	s_cselect_b64 s[4:5], -1, 0
	v_writelane_b32 v254, s4, 53
	s_cmp_eq_u32 s16, 3
	s_nop 0
	v_writelane_b32 v254, s5, 54
	s_cselect_b64 s[4:5], -1, 0
	v_writelane_b32 v254, s4, 55
	s_cmp_eq_u32 s16, 2
	s_nop 0
	v_writelane_b32 v254, s5, 56
	s_cselect_b64 s[4:5], -1, 0
	v_writelane_b32 v254, s4, 57
	s_cmp_eq_u32 s16, 1
	s_nop 0
	v_writelane_b32 v254, s5, 58
	s_cselect_b64 s[4:5], -1, 0
	v_writelane_b32 v254, s4, 59
	s_cmp_eq_u32 s16, 0
	s_nop 0
	v_writelane_b32 v254, s5, 60
	s_cselect_b64 s[4:5], -1, 0
	v_writelane_b32 v254, s4, 61
	s_nop 1
	v_writelane_b32 v254, s5, 62
	s_lshl_b32 s4, s16, 8
	s_add_u32 s2, s2, s4
	s_addc_u32 s3, s3, 0
	s_add_u32 s4, s2, 0x1400
	s_addc_u32 s5, s3, 0
	s_add_u32 s78, s2, 0x2400
	s_addc_u32 s79, s3, 0
	s_add_u32 s2, s0, 0xe3400
	v_writelane_b32 v254, s4, 63
	s_addc_u32 s3, s1, 0
	s_add_u32 s88, s0, 0xe3500
	v_writelane_b32 v255, s5, 0
	v_writelane_b32 v255, s2, 1
	s_addc_u32 s89, s1, 0
	s_add_i32 s0, 0, 0x23fc0
	v_writelane_b32 v255, s3, 2
	v_writelane_b32 v255, s0, 3
	s_add_i32 s0, 0, 0x23fc4
	v_writelane_b32 v255, s0, 4
	s_add_i32 s0, 0, 0x10800
	v_writelane_b32 v255, s0, 5
	v_cmp_eq_u32_e64 s[0:1], 0, v0
	s_nop 1
	v_writelane_b32 v255, s0, 6
	s_nop 1
	v_writelane_b32 v255, s1, 7
	s_mov_b32 s0, s9
	v_writelane_b32 v255, s0, 8
	s_nop 1
	v_writelane_b32 v255, s1, 9
	v_writelane_b32 v255, s94, 10
	s_nop 1
	v_writelane_b32 v255, s95, 11
	v_writelane_b32 v255, s84, 12
	v_writelane_b32 v255, s96, 13
	s_nop 1
	v_writelane_b32 v255, s97, 14
	v_writelane_b32 v255, s78, 15
	s_nop 1
	v_writelane_b32 v255, s79, 16
	v_writelane_b32 v255, s88, 17
	s_nop 1
	v_writelane_b32 v255, s89, 18
	v_writelane_b32 v255, s83, 19
	v_writelane_b32 v255, s90, 20
	s_nop 1
	v_writelane_b32 v255, s91, 21
	v_writelane_b32 v255, s92, 22
	s_nop 1
	v_writelane_b32 v255, s93, 23
	v_writelane_b32 v255, s86, 24
	s_nop 1
	v_writelane_b32 v255, s87, 25
	s_branch .LBB0_159

;     __device__ __forceinline__ void operator()(f32x4 (&acc)[2][2][4][2], const Unit& u, int wr, int wc, int fr, int fq) const {
;     ...
;         float gq[2][4], inv[2][2];
;         { const float* gsrc = u.pn < 4 ? qg : kg;
; #pragma unroll
;           for (int n = 0; n < 2; ++n) {
; #pragma unroll
;             for (int e = 0; e < 4; ++e) { const int p = wc * 32 + 8 * fq + 4 * n + e; gq[n][e] = gsrc[(p >> 6) * 64 + (p & 1) * 32 + ((p & 63) >> 1)]; }
; #pragma unroll
;             for (int pr = 0; pr < 2; ++pr) inv[n][pr] = __builtin_amdgcn_exp2f(-(float)(16 * (wc & 1) + 4 * fq + 2 * n + pr) * 0.4152410118609203f); } }
;         const int headbase = (u.pn & 1) * 2;
; #pragma unroll
;         for (int ai = 0; ai < 2; ++ai)
; #pragma unroll
;             for (int m = 0; m < 4; ++m) { const int rl = wr * 64 + fr + ai * HALF + m * 16, row = rowt + rl;
;                 int kvrow; float cs[2][2], sn[2][2];
;                 if (is_lat) { const int t = row & (SEQ - 1); kvrow = b * SKV + CTXL + t; const float pos = (float)((wc >> 1) ? (t & 63) : (t >> 6));
; #pragma unroll
;                     for (int n = 0; n < 2; ++n)
; #pragma unroll
;                         for (int pr = 0; pr < 2; ++pr) { const float a = pos * inv[n][pr]; cs[n][pr] = __cosf(a); sn[n][pr] = __sinf(a); } }
.LBB0_637:
	s_load_dwordx4 s[20:23], s[0:1], 0x68
	v_add_u32_e32 v0, s68, v174
	s_and_b64 s[16:17], s[78:79], exec
	s_waitcnt lgkmcnt(0)
	v_and_b32_e32 v2, 0xffffffc0, v0
	v_lshrrev_b32_e32 v0, 1, v0
	s_cselect_b32 s16, s20, s22
	v_and_b32_e32 v0, 28, v0
	s_cselect_b32 s8, s21, s23
	s_add_u32 s16, s16, s2
	v_or_b32_e32 v0, v0, v2
	s_addc_u32 s17, s8, s3
	v_ashrrev_i32_e32 v1, 31, v0
	v_lshl_add_u64 v[4:5], v[0:1], 2, s[16:17]
	v_ashrrev_i32_e32 v1, 31, v2
	v_lshl_add_u64 v[6:7], v[0:1], 2, s[16:17]
	global_load_dwordx4 v[0:3], v[6:7], off offset:128
	global_load_dword v8, v[4:5], off
	s_nop 0
	global_load_dwordx3 v[4:6], v[6:7], off offset:4
	s_waitcnt vmcnt(0)
	s_and_b64 s[16:17], s[78:79], exec
	s_cselect_b32 s16, 0x3e0293ee, 1.0
	v_mul_f32_e32 v0, s16, v0
	v_mul_f32_e32 v1, s16, v1
	v_mul_f32_e32 v2, s16, v2
	v_mul_f32_e32 v3, s16, v3
	v_mul_f32_e32 v8, s16, v8
	v_mul_f32_e32 v4, s16, v4
	v_mul_f32_e32 v5, s16, v5
	v_mul_f32_e32 v6, s16, v6
	v_add_u32_e32 v9, s4, v178
	v_or_b32_e32 v68, 1, v9
	v_cvt_f32_i32_e32 v7, v9
	v_cvt_f32_i32_e32 v68, v68
	v_or_b32_e32 v69, 2, v9
	v_or_b32_e32 v9, 3, v9
	v_cvt_f32_i32_e32 v69, v69
	v_cvt_f32_i32_e32 v9, v9
	v_mul_f32_e32 v68, 0xbed49a78, v68
	v_mul_f32_e32 v7, 0xbed49a78, v7
	v_exp_f32_e32 v192, v68
	v_mul_f32_e32 v68, 0xbed49a78, v69
	v_mul_f32_e32 v9, 0xbed49a78, v9
	v_exp_f32_e32 v7, v7
	v_exp_f32_e32 v185, v68
	v_exp_f32_e32 v184, v9
	s_mul_i32 s59, s76, 0x2100
	v_cndmask_b32_e64 v9, 0, 1, s[74:75]
	s_addk_i32 s59, 0x100
	v_and_b32_e32 v69, 63, v193
	v_cmp_ne_u32_e64 s[42:43], 1, v9
	s_andn2_b64 vcc, exec, s[74:75]
	s_mov_b64 s[44:45], -1
	s_cbranch_vccnz .LBB0_639
	v_bfe_u32 v9, v176, 6, 7
	v_cndmask_b32_e64 v9, v69, v9, s[38:39]
	v_cvt_f32_ubyte0_e32 v9, v9
	v_mul_f32_e32 v68, v7, v9
	v_mul_f32_e32 v68, 0.15915494, v68
	v_cos_f32_e32 v82, v68
	v_sin_f32_e32 v86, v68
	v_mul_f32_e32 v68, v192, v9
	v_mul_f32_e32 v68, 0.15915494, v68
	v_cos_f32_e32 v80, v68
	v_sin_f32_e32 v84, v68
	v_mul_f32_e32 v68, v185, v9
	v_mul_f32_e32 v9, v184, v9
	v_mul_f32_e32 v68, 0.15915494, v68
	v_mul_f32_e32 v9, 0.15915494, v9
	v_cos_f32_e32 v76, v68
	v_sin_f32_e32 v78, v68
	v_cos_f32_e32 v70, v9
	v_sin_f32_e32 v68, v9
	v_and_b32_e32 v9, 0x1fff, v176
	v_add_u32_e32 v154, s59, v9
	s_mov_b64 s[44:45], 0

; __global__ void __launch_bounds__(NWAVES * 64, 2) fwd_kernel(Args args) {
;     ...
;                 float mnC;
;                 { const float* qgp = A_->attn_q_g + (size_t)jl * 128; const float* kgp = A_->attn_k_g + (size_t)jl * 128;
;                   float mq = fmaxf(fabsf(qgp[lane]), fabsf(qgp[64 + lane])), mk = fmaxf(fabsf(kgp[lane]), fabsf(kgp[64 + lane]));
; #pragma unroll
;                   for (int o = 1; o < 64; o <<= 1) { mq = fmaxf(mq, __shfl_xor(mq, o)); mk = fmaxf(mk, __shfl_xor(mk, o)); }
;                   mnC = __builtin_bit_cast(float, __builtin_amdgcn_readfirstlane(__builtin_bit_cast(int, -(11.3138f * 1.01f * mq * mk + 0.05f) * 1.4426950408889634f))); }
;                 for (int idx = bx; idx < 512; idx += G) {
.LBB0_1033:
	s_andn2_b64 vcc, exec, s[0:1]
	s_cbranch_vccnz .LBB0_1109
	v_readlane_b32 s0, v255, 8
	v_readlane_b32 s1, v255, 9
	s_mul_hi_u32 s2, s0, 0xaaaaaaab
	v_mov_b32_e32 v170, v215
	s_mov_b32 s4, s84
	s_mov_b32 s5, s82
	s_mov_b64 s[0:1], s[94:95]
	s_waitcnt lgkmcnt(0)
	s_load_dwordx4 s[12:15], s[0:1], 0x68
	s_lshl_b32 s2, s2, 6
	s_and_b32 s8, s2, 0xffffff80
	s_lshl_b64 s[2:3], s[8:9], 2
	s_waitcnt vmcnt(0)
	v_and_b32_e32 v0, 63, v170
	s_waitcnt lgkmcnt(0)
	s_add_u32 s6, s12, s2
	s_addc_u32 s7, s13, s3
	v_lshlrev_b32_e32 v0, 2, v0
	s_add_u32 s2, s14, s2
	global_load_dword v1, v0, s[6:7]
	global_load_dword v2, v0, s[6:7] offset:256
	s_addc_u32 s3, s15, s3
	global_load_dword v3, v0, s[2:3] offset:256
	s_nop 0
	global_load_dword v0, v0, s[2:3]
	s_waitcnt vmcnt(0)
	v_and_b32_e32 v4, 64, v246
	v_xor_b32_e32 v5, 1, v246
	v_add_u32_e32 v4, 64, v4
	v_cmp_lt_i32_e32 vcc, v5, v4
	v_xor_b32_e32 v6, 2, v246
	v_xor_b32_e32 v7, 4, v246
	v_cndmask_b32_e32 v5, v246, v5, vcc
	v_lshlrev_b32_e32 v5, 2, v5
	v_cmp_lt_i32_e32 vcc, v6, v4
	v_xor_b32_e32 v8, 8, v246
	v_xor_b32_e32 v9, 16, v246
	v_xor_b32_e32 v10, 32, v246
	s_cmpk_lt_i32 s4, 0x200
	v_max_f32_e64 v1, |v1|, |v1|
	v_max_f32_e64 v2, |v2|, |v2|
	v_max_f32_e32 v1, v1, v2
	v_max_f32_e64 v2, |v3|, |v3|
	v_max_f32_e64 v0, |v0|, |v0|
	ds_bpermute_b32 v3, v5, v1
	v_max_f32_e32 v0, v0, v2
	ds_bpermute_b32 v2, v5, v0
	v_cndmask_b32_e32 v5, v246, v6, vcc
	v_lshlrev_b32_e32 v5, 2, v5
	s_waitcnt lgkmcnt(1)
	v_max_f32_e32 v3, v3, v3
	v_max_f32_e32 v1, v1, v3
	s_waitcnt lgkmcnt(0)
	v_max_f32_e32 v2, v2, v2
	ds_bpermute_b32 v3, v5, v1
	v_max_f32_e32 v0, v0, v2
	ds_bpermute_b32 v2, v5, v0
	v_cmp_lt_i32_e32 vcc, v7, v4
	s_waitcnt lgkmcnt(1)
	v_max_f32_e32 v3, v3, v3
	v_cndmask_b32_e32 v5, v246, v7, vcc
	v_lshlrev_b32_e32 v5, 2, v5
	v_max_f32_e32 v1, v1, v3
	s_waitcnt lgkmcnt(0)
	v_max_f32_e32 v2, v2, v2
	ds_bpermute_b32 v3, v5, v1
	v_max_f32_e32 v0, v0, v2
	ds_bpermute_b32 v2, v5, v0
	v_cmp_lt_i32_e32 vcc, v8, v4
	s_waitcnt lgkmcnt(1)
	v_max_f32_e32 v3, v3, v3
	v_cndmask_b32_e32 v5, v246, v8, vcc
	v_lshlrev_b32_e32 v5, 2, v5
	v_max_f32_e32 v1, v1, v3
	s_waitcnt lgkmcnt(0)
	v_max_f32_e32 v2, v2, v2
	ds_bpermute_b32 v3, v5, v1
	v_max_f32_e32 v0, v0, v2
	ds_bpermute_b32 v2, v5, v0
	v_cmp_lt_i32_e32 vcc, v9, v4
	s_waitcnt lgkmcnt(1)
	v_max_f32_e32 v3, v3, v3
	v_cndmask_b32_e32 v5, v246, v9, vcc
	v_lshlrev_b32_e32 v5, 2, v5
	v_max_f32_e32 v1, v1, v3
	s_waitcnt lgkmcnt(0)
	v_max_f32_e32 v2, v2, v2
	ds_bpermute_b32 v3, v5, v1
	v_max_f32_e32 v0, v0, v2
	ds_bpermute_b32 v2, v5, v0
	v_cmp_lt_i32_e32 vcc, v10, v4
	s_waitcnt lgkmcnt(1)
	v_max_f32_e32 v3, v3, v3
	v_cndmask_b32_e32 v4, v246, v10, vcc
	v_lshlrev_b32_e32 v4, 2, v4
	v_max_f32_e32 v1, v1, v3
	s_waitcnt lgkmcnt(0)
	v_max_f32_e32 v2, v2, v2
	ds_bpermute_b32 v3, v4, v1
	v_max_f32_e32 v0, v0, v2
	ds_bpermute_b32 v2, v4, v0
	s_waitcnt lgkmcnt(1)
	v_max_f32_e32 v3, v3, v3
	v_max_f32_e32 v1, v1, v3
	s_waitcnt lgkmcnt(0)
	v_max_f32_e32 v2, v2, v2
	v_mul_f32_e32 v1, 0x4136d4bd, v1
	v_max_f32_e32 v0, v0, v2
	v_mul_f32_e32 v0, v0, v1
	s_nop 0
	v_readfirstlane_b32 s2, v0
	s_cbranch_scc0 .LBB0_1043
	v_mov_b32_e32 v0, 0x3d4ccccd
	v_add_f32_e32 v0, s2, v0
	v_mov_b32_e32 v152, 0
	v_mov_b32_e32 v154, v152
	v_mov_b32_e32 v155, v152
	v_mov_b32_e32 v156, v152
	v_mov_b32_e32 v157, v152
	s_mov_b32 s8, s4
	s_branch .LBB0_1037

; __device__ __forceinline__ int v_st(int k, int c) { const int kk = (k & ~0xC) | ((k & 4) << 1) | ((k & 8) >> 1); return ((kk >> 3) * 4 + (c >> 5)) * 512 + ((kk & 7) * 32 + (c & 31)) * 2; }
; __device__ __forceinline__ void partialSM(f32x16& p0, f32x16& p1, float mnC) {
;   constexpr float C = SCALE * 1.4426950408889634f;
; #pragma unroll
;   for (int r = 0; r < 16; ++r) p0[r] = fmaf(p0[r], C, mnC);
; #pragma unroll
;   for (int r = 0; r < 16; ++r) p1[r] = fmaf(p1[r], C, mnC);
; #pragma unroll
;   for (int r = 0; r < 16; ++r) p0[r] = __builtin_amdgcn_exp2f(p0[r]);
; }
; __device__ __forceinline__ void finishSM(f32x16& p0, f32x16& p1, float& l_reg, bf16x8& pa0, bf16x8& pa1, bf16x8& pa2, bf16x8& pa3) {
; #pragma unroll
;   for (int r = 0; r < 16; ++r) p1[r] = __builtin_amdgcn_exp2f(p1[r]);
; __device__ __forceinline__ void attn_dense_body(const bf16* __restrict__ Qb, const bf16* __restrict__ Kh, const bf16* __restrict__ Vh,
;                                                 bf16* __restrict__ Ob, int seq, char* lds, const int tid, const float mnC) {
;   const int wid = tid >> 6, lane = tid & 63, r32 = lane & 31, hi = lane >> 5;
;   bf16* V_lds = (bf16*)lds; bf16* K_lds = (bf16*)(lds + 2 * SHM_V);
;   float* ws = (float*)(lds + 2 * SHM_V + 2 * SHM_K) + wid * 64; float* li_l = ws;
;   float l_reg = 0; f32x16 o[4] = {}; bf16x8 qr[8];
;   const bf16* Qw = Qb + (long)(wid * QBLK + r32) * LDQ + hi * 8;
; #pragma unroll
;   for (int d0 = 0; d0 < 8; ++d0) qr[d0] = ld8(Qw + d0 * 16);
;   const int sr = tid >> 4, sc = (tid & 15) * 8, vst0 = v_st(sr, sc), vst1 = v_st(32 + sr, sc);
;   const int vb0 = (int)(uintptr_t)V_lds + v_rd_base(lane);
;   bf16x8 s0_vs0, s0_vs1, s0_ks0, s0_ks1;
;     ...
;   f32x16 pA0, pA1, pB0, pB1; bf16x8 pa0, pa1, pa2, pa3; const int NT = seq / KVBLK;
;   SLOAD0(0);
;   bf16x8 t1_vs0 = ld8(&Vh[(long)(KVBLK + sr) * LDK + sc]), t1_vs1 = ld8(&Vh[(long)(KVBLK + 32 + sr) * LDK + sc]);
;   bf16x8 t1_ks0 = ld8(&Kh[(long)(KVBLK + sr) * LDK + sc]), t1_ks1 = ld8(&Kh[(long)(KVBLK + 32 + sr) * LDK + sc]);
;   asm volatile("s_waitcnt vmcnt(4)" ::: "memory"); SWRITE0(0); __syncthreads();
;   qkt(pA0, pA1, K_lds, qr, r32, hi); partialSM(pA0, pA1, mnC);
;   s0_vs0 = t1_vs0; s0_vs1 = t1_vs1; s0_ks0 = t1_ks0; s0_ks1 = t1_ks1;
;   SWAIT(); SWRITE0(1); __syncthreads();
;   if (__builtin_amdgcn_readfirstlane(wid) >= 4) __builtin_amdgcn_s_setprio(1);
.LBB0_1039:
	s_lshr_b32 s12, s8, 2
	v_and_b32_e32 v159, 63, v174
	s_and_b32 s12, s12, 1
	s_and_b32 s13, s4, 3
	v_mov_b32_e32 v153, v152
	s_nop 5
	v_pk_fma_f32 v[168:169], v[0:1], s[26:27], v[156:157] op_sel_hi:[1,0,1]
	s_mul_i32 s12, s12, 0x840000
	s_lshl_b32 s13, s13, 8
	v_lshlrev_b32_e32 v1, 4, v159
	v_pk_fma_f32 v[166:167], v[2:3], s[26:27], v[152:153] op_sel_hi:[1,0,1]
	s_or_b32 s13, s13, s12
	v_lshlrev_b32_e32 v0, 3, v159
	v_and_b32_e32 v1, 0xc0, v1
	v_lshlrev_b32_e32 v2, 1, v159
	v_and_or_b32 v1, v0, 24, v1
	v_and_b32_e32 v2, 32, v2
	v_and_b32_e32 v0, 0x100, v0
	s_cmp_lg_u32 0, -1
	v_or3_b32 v0, v1, v2, v0
	s_cselect_b32 s14, 0, 0
	v_fmamk_f32 v16, v16, 0x3f800000, v152
	v_fmamk_f32 v17, v17, 0x3f800000, v152
	v_fmamk_f32 v18, v18, 0x3f800000, v152
	v_fmamk_f32 v19, v19, 0x3f800000, v152
	v_fmamk_f32 v20, v20, 0x3f800000, v152
	v_fmamk_f32 v21, v21, 0x3f800000, v152
	v_fmamk_f32 v22, v22, 0x3f800000, v152
	v_fmamk_f32 v23, v23, 0x3f800000, v152
	v_fmamk_f32 v24, v24, 0x3f800000, v152
	v_fmamk_f32 v25, v25, 0x3f800000, v152
	v_fmamk_f32 v26, v26, 0x3f800000, v152
	v_fmamk_f32 v27, v27, 0x3f800000, v152
	v_fmamk_f32 v28, v28, 0x3f800000, v152
	v_fmamk_f32 v29, v29, 0x3f800000, v152
	v_fmamk_f32 v30, v30, 0x3f800000, v152
	v_fmamk_f32 v31, v31, 0x3f800000, v152
	v_add_u32_e32 v173, s14, v0
	s_addk_i32 s14, 0x4000
	v_pk_fma_f32 v[144:145], v[14:15], s[26:27], v[152:153] op_sel_hi:[1,0,1]
	v_pk_fma_f32 v[146:147], v[12:13], s[26:27], v[152:153] op_sel_hi:[1,0,1]
	v_pk_fma_f32 v[148:149], v[10:11], s[26:27], v[152:153] op_sel_hi:[1,0,1]
	v_pk_fma_f32 v[162:163], v[8:9], s[26:27], v[152:153] op_sel_hi:[1,0,1]
	v_pk_fma_f32 v[150:151], v[6:7], s[26:27], v[152:153] op_sel_hi:[1,0,1]
	v_pk_fma_f32 v[164:165], v[4:5], s[26:27], v[152:153] op_sel_hi:[1,0,1]
	v_exp_f32_e32 v199, v16
	v_exp_f32_e32 v201, v17
	v_exp_f32_e32 v198, v18
	v_exp_f32_e32 v203, v19
	v_exp_f32_e32 v200, v20
	v_exp_f32_e32 v202, v21
	v_exp_f32_e32 v196, v22
	v_exp_f32_e32 v197, v23
	v_exp_f32_e32 v193, v24
	v_exp_f32_e32 v195, v25
	v_exp_f32_e32 v192, v26
	v_exp_f32_e32 v194, v27
	v_exp_f32_e32 v189, v28
	v_exp_f32_e32 v191, v29
	v_exp_f32_e32 v188, v30
	v_exp_f32_e32 v190, v31
	v_add_u32_e32 v153, s14, v0
	v_and_b32_e32 v0, 15, v174
	s_add_u32 s14, s2, s13
	v_lshl_or_b32 v32, v0, 4, v32
	s_addc_u32 s15, s3, 0
	v_lshl_add_u64 v[0:1], s[14:15], 0, v[32:33]
	s_mov_b64 s[14:15], 0xeb38000
	v_mov_b32_e32 v187, 0
	s_mov_b32 s12, -1
	v_lshl_add_u64 v[160:161], v[0:1], 0, s[14:15]
	v_mov_b32_e32 v0, 0
	v_mov_b32_e32 v1, v187
	v_mov_b32_e32 v2, v187
	v_mov_b32_e32 v3, v187
	v_mov_b32_e32 v4, v187
	v_mov_b32_e32 v5, v187
	v_mov_b32_e32 v6, v187
	v_mov_b32_e32 v7, v187
	v_mov_b32_e32 v8, v187
	v_mov_b32_e32 v9, v187
	v_mov_b32_e32 v10, v187
	v_mov_b32_e32 v11, v187
	v_mov_b32_e32 v12, v187
	v_mov_b32_e32 v13, v187
	v_mov_b32_e32 v14, v187
	v_mov_b32_e32 v15, v187
	v_mov_b32_e32 v16, 0
	v_mov_b32_e32 v17, v187
	v_mov_b32_e32 v18, v187
	v_mov_b32_e32 v19, v187
	v_mov_b32_e32 v20, v187
	v_mov_b32_e32 v21, v187
	v_mov_b32_e32 v22, v187
	v_mov_b32_e32 v23, v187
	v_mov_b32_e32 v24, v187
	v_mov_b32_e32 v25, v187
	v_mov_b32_e32 v26, v187
	v_mov_b32_e32 v27, v187
	v_mov_b32_e32 v28, v187
	v_mov_b32_e32 v29, v187
	v_mov_b32_e32 v30, v187
	v_mov_b32_e32 v31, v187
	v_mov_b32_e32 v32, 0
	v_mov_b32_e32 v33, v187
	v_mov_b32_e32 v34, v187
	v_mov_b32_e32 v35, v187
	v_mov_b32_e32 v36, v187
	v_mov_b32_e32 v37, v187
	v_mov_b32_e32 v38, v187
	v_mov_b32_e32 v39, v187
	v_mov_b32_e32 v40, v187
	v_mov_b32_e32 v41, v187
	v_mov_b32_e32 v42, v187
	v_mov_b32_e32 v43, v187
	v_mov_b32_e32 v44, v187
	v_mov_b32_e32 v45, v187
	v_mov_b32_e32 v46, v187
	v_mov_b32_e32 v47, v187
	v_mov_b32_e32 v48, 0
	v_mov_b32_e32 v49, v187
	v_mov_b32_e32 v50, v187
	v_mov_b32_e32 v51, v187
	v_mov_b32_e32 v52, v187
	v_mov_b32_e32 v53, v187
	v_mov_b32_e32 v54, v187
	v_mov_b32_e32 v55, v187
	v_mov_b32_e32 v56, v187
	v_mov_b32_e32 v57, v187
	v_mov_b32_e32 v58, v187
	v_mov_b32_e32 v59, v187
	v_mov_b32_e32 v60, v187
	v_mov_b32_e32 v61, v187
	v_mov_b32_e32 v62, v187
	v_mov_b32_e32 v63, v187
	v_lshrrev_b32_e32 v216, 6, v174
	v_lshrrev_b32_e32 v217, 4, v159
	v_and_b32_e32 v218, 15, v159
	v_readfirstlane_b32 s98, v216
	v_xor_b32_e32 v218, v218, v217
	v_and_b32_e32 v219, 1, v216
	v_lshlrev_b32_e32 v219, 3, v219
	v_xor_b32_e32 v218, v218, v219
	v_lshlrev_b32_e32 v218, 4, v218
	v_lshl_or_b32 v218, v217, 10, v218
	v_lshl_or_b32 v216, v216, 13, v218
	v_xor_b32_e32 v217, 64, v216
	v_add_u32_e32 v217, 0x1000, v217
	s_and_b32 s99, s98, 1
	s_lshl_b32 s99, s99, 2
	s_lshr_b32 s100, s98, 1
	s_lshl_b32 s100, s100, 4
	s_or_b32 s99, s99, s100
	s_lshl_b32 s99, s99, 10
	v_bfe_u32 v218, v159, 2, 2
	v_bfe_u32 v219, v159, 4, 1
	v_lshl_or_b32 v218, v219, 3, v218
	v_lshlrev_b32_e32 v218, 10, v218
	v_lshrrev_b32_e32 v219, 5, v159
	v_lshl_or_b32 v218, v219, 6, v218
	v_and_b32_e32 v219, 3, v159
	v_lshl_or_b32 v218, v219, 4, v218
	v_add_u32_e32 v218, s99, v218
	v_add_u32_e32 v219, 0x80, v218
	s_lshl_b32 s98, s98, 11
	s_bfe_u32 s100, s8, 0x10002
	s_mul_i32 s100, s100, 0x840000
	s_and_b32 s101, s8, 3
	s_lshl_b32 s101, s101, 8
	s_add_u32 s100, s100, s101
	s_add_u32 s14, s2, s100
	s_addc_u32 s15, s3, 0
	s_add_u32 s16, s14, 0xeb10000
	s_addc_u32 s17, s15, 0
	s_add_u32 s14, s14, 0xda20000
	s_addc_u32 s15, s15, 0
	v_mov_b32_e32 v136, 0
	v_mov_b32_e32 v137, 0
	v_mov_b32_e32 v138, 0
	v_mov_b32_e32 v139, 0
	v_mov_b32_e32 v140, 0
	v_mov_b32_e32 v141, 0
	v_mov_b32_e32 v142, 0
	v_mov_b32_e32 v143, 0
	v_mov_b32_e32 v208, 0
	v_mov_b32_e32 v209, 0
	v_mov_b32_e32 v210, 0
	v_mov_b32_e32 v211, 0
	v_mov_b32_e32 v228, 0
	v_mov_b32_e32 v229, 0
	v_mov_b32_e32 v230, 0
	v_mov_b32_e32 v231, 0
	v_mov_b32_e32 v232, 0
	v_mov_b32_e32 v233, 0
	v_mov_b32_e32 v234, 0
	v_mov_b32_e32 v235, 0
	v_mov_b32_e32 v236, 0
	v_mov_b32_e32 v237, 0
	v_mov_b32_e32 v238, 0
	v_mov_b32_e32 v239, 0
	v_mov_b32_e32 v240, 0
	v_mov_b32_e32 v241, 0
	v_mov_b32_e32 v242, 0
	v_mov_b32_e32 v243, 0
	v_mov_b32_e32 v204, 0
	v_mov_b32_e32 v205, 0
	v_mov_b32_e32 v206, 0
	v_mov_b32_e32 v207, 0
	v_exp_f32_e32 v168, v168
	v_exp_f32_e32 v169, v169
	v_exp_f32_e32 v166, v166
	v_exp_f32_e32 v167, v167
	v_exp_f32_e32 v164, v164
	v_exp_f32_e32 v165, v165
	v_exp_f32_e32 v150, v150
	v_exp_f32_e32 v151, v151
	v_exp_f32_e32 v162, v162
	v_exp_f32_e32 v163, v163
	v_exp_f32_e32 v148, v148
	v_exp_f32_e32 v149, v149
	v_exp_f32_e32 v146, v146
	v_exp_f32_e32 v147, v147
	v_exp_f32_e32 v144, v144
	v_exp_f32_e32 v145, v145
	v_add_u32_e32 v153, 0x10000, v173
	s_add_i32 m0, s98, 0x10000
	s_nop 0
	global_load_lds_dwordx4 v218, s[16:17]
	s_add_i32 m0, s98, 0x10400
	s_nop 0
	global_load_lds_dwordx4 v219, s[16:17]
	s_add_i32 m0, s98, 0x4000
	s_nop 0
	global_load_lds_dwordx4 v216, s[14:15]
	s_add_i32 m0, s98, 0x4400
	s_nop 0
	global_load_lds_dwordx4 v217, s[14:15]
	s_add_u32 s14, s14, 0x10000
	s_addc_u32 s15, s15, 0
	s_add_u32 s16, s16, 0x10000
	s_addc_u32 s17, s17, 0
	s_mov_b32 s12, 43
; #define SBAR() __builtin_amdgcn_sched_barrier(0)
; __device__ __forceinline__ void qkt(f32x16& p0, f32x16& p1, const bf16* Ks, const bf16x8* qr, int r32, int hi) {
;   p0 = f32x16{}; p1 = f32x16{};
; #pragma unroll
;   for (int d0 = 0; d0 < 8; ++d0) { int cb = (d0 * 16 + hi * 8) * 2;
;     bf16x8 b0 = *reinterpret_cast<const bf16x8*>((const char*)Ks + KSWZ(r32, cb));
;     bf16x8 b1 = *reinterpret_cast<const bf16x8*>((const char*)Ks + KSWZ(32 + r32, cb));
;     p0 = __builtin_amdgcn_mfma_f32_32x32x16_bf16(b0, qr[d0], p0, 0, 0, 0);
;     p1 = __builtin_amdgcn_mfma_f32_32x32x16_bf16(b1, qr[d0], p1, 0, 0, 0); }
; }
; __device__ __forceinline__ int v_st(int k, int c) { const int kk = (k & ~0xC) | ((k & 4) << 1) | ((k & 8) >> 1); return ((kk >> 3) * 4 + (c >> 5)) * 512 + ((kk & 7) * 32 + (c & 31)) * 2; }
; __device__ __forceinline__ int v_rd_base(int lane) { return ((lane & 3) << 3) | (((lane >> 2) & 3) << 6) | (((lane >> 4) & 1) << 5) | (((lane >> 5) & 1) << 8); }
; template <int OFF> __device__ __forceinline__ s16x4 tr_read(int vb) {
;   s16x4 r; asm volatile("ds_read_b64_tr_b16 %0, %1 offset:%2" : "=&v"(r) : "v"(vb), "i"(OFF) : "memory"); return r;
; }
; template <int D0> __device__ __forceinline__ void pv_one(f32x16& od, int vb, bf16x8 pa0, bf16x8 pa1, bf16x8 pa2, bf16x8 pa3) {
;   const s16x4 l0 = tr_read<v_rd_off(D0, 0, 0)>(vb), h0 = tr_read<v_rd_off(D0, 0, 1)>(vb), l1 = tr_read<v_rd_off(D0, 1, 0)>(vb), h1 = tr_read<v_rd_off(D0, 1, 1)>(vb);
;   const s16x4 l2 = tr_read<v_rd_off(D0, 2, 0)>(vb), h2 = tr_read<v_rd_off(D0, 2, 1)>(vb), l3 = tr_read<v_rd_off(D0, 3, 0)>(vb), h3 = tr_read<v_rd_off(D0, 3, 1)>(vb);
;   asm volatile("s_waitcnt lgkmcnt(0)" ::: "memory"); SBAR();
;     ...
;   od = __builtin_amdgcn_mfma_f32_32x32x16_bf16(pa0, PK(l0, h0), od, 0, 0, 0);
;   od = __builtin_amdgcn_mfma_f32_32x32x16_bf16(pa1, PK(l1, h1), od, 0, 0, 0);
;   od = __builtin_amdgcn_mfma_f32_32x32x16_bf16(pa2, PK(l2, h2), od, 0, 0, 0);
;   od = __builtin_amdgcn_mfma_f32_32x32x16_bf16(pa3, PK(l3, h3), od, 0, 0, 0);
;     ...
; }
; __device__ __forceinline__ void pv_d0(f32x16* o, int vb, bf16x8 pa0, bf16x8 pa1, bf16x8 pa2, bf16x8 pa3) {
;   pv_one<0>(o[0], vb, pa0, pa1, pa2, pa3); pv_one<1>(o[1], vb, pa0, pa1, pa2, pa3); pv_one<2>(o[2], vb, pa0, pa1, pa2, pa3); pv_one<3>(o[3], vb, pa0, pa1, pa2, pa3);
.LBB0_1040:
	ds_read_b128 v[128:131], v179 offset:49152
	ds_read_b128 v[132:135], v179 offset:57344
	ds_read_b128 v[220:223], v182 offset:49152
	ds_read_b128 v[224:227], v182 offset:57344
	v_mfma_f32_32x32x16_bf16 v[48:63], v[136:139], v[232:235], v[48:63]
	s_add_i32 m0, s98, 0x8000
	s_nop 0
	global_load_lds_dwordx4 v216, s[14:15]
	v_mfma_f32_32x32x16_bf16 v[48:63], v[140:143], v[236:239], v[48:63]
	ds_read_b128 v[232:235], v183 offset:49152
	ds_read_b128 v[236:239], v183 offset:57344
	s_add_i32 m0, s98, 0x8400
	s_nop 0
	global_load_lds_dwordx4 v217, s[14:15]
	v_mfma_f32_32x32x16_bf16 v[48:63], v[208:211], v[240:243], v[48:63]
	s_add_i32 m0, s98, 0x14000
	s_nop 0
	global_load_lds_dwordx4 v218, s[16:17]
	v_mfma_f32_32x32x16_bf16 v[48:63], v[228:231], v[204:207], v[48:63]
	ds_read_b128 v[240:243], v184 offset:49152
	ds_read_b128 v[204:207], v184 offset:57344
	s_add_i32 m0, s98, 0x14400
	s_nop 0
	global_load_lds_dwordx4 v219, s[16:17]
	s_add_u32 s14, s14, 0x10000
	s_addc_u32 s15, s15, 0
	s_add_u32 s16, s16, 0x10000
	s_addc_u32 s17, s17, 0
	s_waitcnt lgkmcnt(7)
	v_mfma_f32_32x32x16_bf16 v[80:95], v[128:131], v[124:127], 0
	v_add_f32_e32 v244, v199, v201
	v_cvt_pk_bf16_f32 v136, v199, v201
	v_add_f32_e32 v244, v198, v244
	v_cvt_pk_bf16_f32 v137, v198, v203
	s_waitcnt lgkmcnt(6)
	v_mfma_f32_32x32x16_bf16 v[64:79], v[132:135], v[124:127], 0
	ds_read_b128 v[128:131], v185 offset:49152
	ds_read_b128 v[132:135], v185 offset:57344
	v_add_f32_e32 v244, v203, v244
	v_cvt_pk_bf16_f32 v138, v200, v202
	v_add_f32_e32 v244, v200, v244
	v_cvt_pk_bf16_f32 v139, v196, v197
	s_waitcnt lgkmcnt(7)
	v_mfma_f32_32x32x16_bf16 v[80:95], v[220:223], v[120:123], v[80:95]
	v_add_f32_e32 v244, v202, v244
	v_cvt_pk_bf16_f32 v140, v193, v195
	v_add_f32_e32 v244, v196, v244
	v_cvt_pk_bf16_f32 v141, v192, v194
	s_waitcnt lgkmcnt(6)
	v_mfma_f32_32x32x16_bf16 v[64:79], v[224:227], v[120:123], v[64:79]
	ds_read_b128 v[220:223], v186 offset:49152
	ds_read_b128 v[224:227], v186 offset:57344
	v_add_f32_e32 v244, v197, v244
	v_cvt_pk_bf16_f32 v142, v189, v191
	v_add_f32_e32 v244, v193, v244
	v_cvt_pk_bf16_f32 v143, v188, v190
	s_waitcnt lgkmcnt(7)
	v_mfma_f32_32x32x16_bf16 v[80:95], v[232:235], v[116:119], v[80:95]
	v_add_f32_e32 v244, v195, v244
	v_cvt_pk_bf16_f32 v208, v168, v169
	v_permlane32_swap_b32_e32 v136, v138
	v_add_f32_e32 v244, v192, v244
	v_cvt_pk_bf16_f32 v209, v166, v167
	s_waitcnt lgkmcnt(6)
	v_mfma_f32_32x32x16_bf16 v[64:79], v[236:239], v[116:119], v[64:79]
	v_add_f32_e32 v244, v194, v244
	v_cvt_pk_bf16_f32 v210, v164, v165
	v_permlane32_swap_b32_e32 v137, v139
	v_add_f32_e32 v244, v189, v244
	v_cvt_pk_bf16_f32 v211, v150, v151
	s_waitcnt lgkmcnt(5)
	v_mfma_f32_32x32x16_bf16 v[80:95], v[240:243], v[112:115], v[80:95]
	v_add_f32_e32 v244, v191, v244
	v_cvt_pk_bf16_f32 v228, v162, v163
	v_permlane32_swap_b32_e32 v140, v142
	v_add_f32_e32 v244, v188, v244
	v_cvt_pk_bf16_f32 v229, v148, v149
	s_waitcnt lgkmcnt(4)
	v_mfma_f32_32x32x16_bf16 v[64:79], v[204:207], v[112:115], v[64:79]
	v_add_f32_e32 v244, v190, v244
	v_cvt_pk_bf16_f32 v230, v146, v147
	v_permlane32_swap_b32_e32 v141, v143
	v_add_f32_e32 v244, v168, v244
	v_cvt_pk_bf16_f32 v231, v144, v145
	s_waitcnt lgkmcnt(3)
	v_mfma_f32_32x32x16_bf16 v[80:95], v[128:131], v[108:111], v[80:95]
	v_add_f32_e32 v244, v169, v244
	v_permlane32_swap_b32_e32 v208, v210
	v_add_f32_e32 v244, v166, v244
	s_waitcnt lgkmcnt(2)
	v_mfma_f32_32x32x16_bf16 v[64:79], v[132:135], v[108:111], v[64:79]
	ds_read_b128 v[128:131], v180 offset:49152
	ds_read_b128 v[132:135], v180 offset:57344
	v_add_f32_e32 v244, v167, v244
	v_permlane32_swap_b32_e32 v209, v211
	v_add_f32_e32 v244, v164, v244
	s_waitcnt lgkmcnt(3)
	v_mfma_f32_32x32x16_bf16 v[80:95], v[220:223], v[104:107], v[80:95]
	v_add_f32_e32 v244, v165, v244
	v_permlane32_swap_b32_e32 v228, v230
	v_add_f32_e32 v244, v150, v244
	s_waitcnt lgkmcnt(2)
	v_mfma_f32_32x32x16_bf16 v[64:79], v[224:227], v[104:107], v[64:79]
	ds_read_b128 v[220:223], v181 offset:49152
	ds_read_b128 v[224:227], v181 offset:57344
	v_add_f32_e32 v244, v151, v244
	v_permlane32_swap_b32_e32 v229, v231
	v_add_f32_e32 v244, v162, v244
	s_waitcnt lgkmcnt(3)
	v_mfma_f32_32x32x16_bf16 v[80:95], v[128:131], v[100:103], v[80:95]
	v_add_f32_e32 v244, v163, v244
	v_add_f32_e32 v244, v148, v244
	ds_read_b64_tr_b16 v[232:233], v173 offset:0
	ds_read_b64_tr_b16 v[234:235], v173 offset:2048
	s_waitcnt lgkmcnt(4)
	v_mfma_f32_32x32x16_bf16 v[64:79], v[132:135], v[100:103], v[64:79]
	v_add_f32_e32 v244, v149, v244
	v_add_f32_e32 v244, v146, v244
	ds_read_b64_tr_b16 v[236:237], v173 offset:4096
	ds_read_b64_tr_b16 v[238:239], v173 offset:6144
	s_waitcnt lgkmcnt(5)
	v_mfma_f32_32x32x16_bf16 v[80:95], v[220:223], v[96:99], v[80:95]
	v_add_f32_e32 v244, v147, v244
	v_add_f32_e32 v244, v144, v244
	ds_read_b64_tr_b16 v[240:241], v173 offset:8192
	ds_read_b64_tr_b16 v[242:243], v173 offset:10240
	s_waitcnt lgkmcnt(6)
	v_mfma_f32_32x32x16_bf16 v[64:79], v[224:227], v[96:99], v[64:79]
	v_add_f32_e32 v244, v145, v244
	v_add_f32_e32 v187, v187, v244
	ds_read_b64_tr_b16 v[204:205], v173 offset:12288
	ds_read_b64_tr_b16 v[206:207], v173 offset:14336
	s_waitcnt lgkmcnt(6)
	v_mfma_f32_32x32x16_bf16 v[0:15], v[136:139], v[232:235], v[0:15]
	ds_read_b64_tr_b16 v[232:233], v173 offset:512
	ds_read_b64_tr_b16 v[234:235], v173 offset:2560
	s_waitcnt lgkmcnt(6)
	v_mfma_f32_32x32x16_bf16 v[0:15], v[140:143], v[236:239], v[0:15]
	ds_read_b64_tr_b16 v[236:237], v173 offset:4608
	ds_read_b64_tr_b16 v[238:239], v173 offset:6656
	v_exp_f32_e32 v199, v80
	v_exp_f32_e32 v201, v81
	v_exp_f32_e32 v198, v82
	s_waitcnt lgkmcnt(6)
; #define SBAR() __builtin_amdgcn_sched_barrier(0)
; __device__ __forceinline__ void qkt(f32x16& p0, f32x16& p1, const bf16* Ks, const bf16x8* qr, int r32, int hi) {
;   p0 = f32x16{}; p1 = f32x16{};
; #pragma unroll
;   for (int d0 = 0; d0 < 8; ++d0) { int cb = (d0 * 16 + hi * 8) * 2;
;     bf16x8 b0 = *reinterpret_cast<const bf16x8*>((const char*)Ks + KSWZ(r32, cb));
;     bf16x8 b1 = *reinterpret_cast<const bf16x8*>((const char*)Ks + KSWZ(32 + r32, cb));
;     p0 = __builtin_amdgcn_mfma_f32_32x32x16_bf16(b0, qr[d0], p0, 0, 0, 0);
;     p1 = __builtin_amdgcn_mfma_f32_32x32x16_bf16(b1, qr[d0], p1, 0, 0, 0); }
; }
; __device__ __forceinline__ int v_st(int k, int c) { const int kk = (k & ~0xC) | ((k & 4) << 1) | ((k & 8) >> 1); return ((kk >> 3) * 4 + (c >> 5)) * 512 + ((kk & 7) * 32 + (c & 31)) * 2; }
; __device__ __forceinline__ int v_rd_base(int lane) { return ((lane & 3) << 3) | (((lane >> 2) & 3) << 6) | (((lane >> 4) & 1) << 5) | (((lane >> 5) & 1) << 8); }
; template <int OFF> __device__ __forceinline__ s16x4 tr_read(int vb) {
;   s16x4 r; asm volatile("ds_read_b64_tr_b16 %0, %1 offset:%2" : "=&v"(r) : "v"(vb), "i"(OFF) : "memory"); return r;
; }
; template <int D0> __device__ __forceinline__ void pv_one(f32x16& od, int vb, bf16x8 pa0, bf16x8 pa1, bf16x8 pa2, bf16x8 pa3) {
;   const s16x4 l0 = tr_read<v_rd_off(D0, 0, 0)>(vb), h0 = tr_read<v_rd_off(D0, 0, 1)>(vb), l1 = tr_read<v_rd_off(D0, 1, 0)>(vb), h1 = tr_read<v_rd_off(D0, 1, 1)>(vb);
;   const s16x4 l2 = tr_read<v_rd_off(D0, 2, 0)>(vb), h2 = tr_read<v_rd_off(D0, 2, 1)>(vb), l3 = tr_read<v_rd_off(D0, 3, 0)>(vb), h3 = tr_read<v_rd_off(D0, 3, 1)>(vb);
;   asm volatile("s_waitcnt lgkmcnt(0)" ::: "memory"); SBAR();
;     ...
;   od = __builtin_amdgcn_mfma_f32_32x32x16_bf16(pa0, PK(l0, h0), od, 0, 0, 0);
;   od = __builtin_amdgcn_mfma_f32_32x32x16_bf16(pa1, PK(l1, h1), od, 0, 0, 0);
;   od = __builtin_amdgcn_mfma_f32_32x32x16_bf16(pa2, PK(l2, h2), od, 0, 0, 0);
;   od = __builtin_amdgcn_mfma_f32_32x32x16_bf16(pa3, PK(l3, h3), od, 0, 0, 0);
;     ...
; }
; __device__ __forceinline__ void pv_d0(f32x16* o, int vb, bf16x8 pa0, bf16x8 pa1, bf16x8 pa2, bf16x8 pa3) {
;   pv_one<0>(o[0], vb, pa0, pa1, pa2, pa3); pv_one<1>(o[1], vb, pa0, pa1, pa2, pa3); pv_one<2>(o[2], vb, pa0, pa1, pa2, pa3); pv_one<3>(o[3], vb, pa0, pa1, pa2, pa3);
	v_mfma_f32_32x32x16_bf16 v[0:15], v[208:211], v[240:243], v[0:15]
	ds_read_b64_tr_b16 v[240:241], v173 offset:8704
	ds_read_b64_tr_b16 v[242:243], v173 offset:10752
	v_exp_f32_e32 v203, v83
	v_exp_f32_e32 v200, v84
	v_exp_f32_e32 v202, v85
	s_waitcnt lgkmcnt(6)
	v_mfma_f32_32x32x16_bf16 v[0:15], v[228:231], v[204:207], v[0:15]
	ds_read_b64_tr_b16 v[204:205], v173 offset:12800
	ds_read_b64_tr_b16 v[206:207], v173 offset:14848
	v_exp_f32_e32 v196, v86
	v_exp_f32_e32 v197, v87
	v_exp_f32_e32 v193, v88
	s_waitcnt lgkmcnt(6)
	v_mfma_f32_32x32x16_bf16 v[16:31], v[136:139], v[232:235], v[16:31]
	ds_read_b64_tr_b16 v[232:233], v173 offset:1024
	ds_read_b64_tr_b16 v[234:235], v173 offset:3072
	v_exp_f32_e32 v195, v89
	v_exp_f32_e32 v192, v90
	v_exp_f32_e32 v194, v91
	s_waitcnt lgkmcnt(6)
	v_mfma_f32_32x32x16_bf16 v[16:31], v[140:143], v[236:239], v[16:31]
	ds_read_b64_tr_b16 v[236:237], v173 offset:5120
	ds_read_b64_tr_b16 v[238:239], v173 offset:7168
	v_exp_f32_e32 v189, v92
	v_exp_f32_e32 v191, v93
	v_exp_f32_e32 v188, v94
	s_waitcnt lgkmcnt(6)
	v_mfma_f32_32x32x16_bf16 v[16:31], v[208:211], v[240:243], v[16:31]
	ds_read_b64_tr_b16 v[240:241], v173 offset:9216
	ds_read_b64_tr_b16 v[242:243], v173 offset:11264
	v_exp_f32_e32 v190, v95
	v_exp_f32_e32 v168, v64
	v_exp_f32_e32 v169, v65
	s_waitcnt lgkmcnt(6)
	v_mfma_f32_32x32x16_bf16 v[16:31], v[228:231], v[204:207], v[16:31]
	ds_read_b64_tr_b16 v[204:205], v173 offset:13312
	ds_read_b64_tr_b16 v[206:207], v173 offset:15360
	v_exp_f32_e32 v166, v66
	v_exp_f32_e32 v167, v67
	v_exp_f32_e32 v164, v68
	s_waitcnt lgkmcnt(6)
	v_mfma_f32_32x32x16_bf16 v[32:47], v[136:139], v[232:235], v[32:47]
	ds_read_b64_tr_b16 v[232:233], v173 offset:1536
	ds_read_b64_tr_b16 v[234:235], v173 offset:3584
	v_exp_f32_e32 v165, v69
	v_exp_f32_e32 v150, v70
	v_exp_f32_e32 v151, v71
	s_waitcnt lgkmcnt(6)
	v_mfma_f32_32x32x16_bf16 v[32:47], v[140:143], v[236:239], v[32:47]
	ds_read_b64_tr_b16 v[236:237], v173 offset:5632
	ds_read_b64_tr_b16 v[238:239], v173 offset:7680
	v_exp_f32_e32 v162, v72
	v_exp_f32_e32 v163, v73
	v_exp_f32_e32 v148, v74
	s_waitcnt lgkmcnt(6)
	v_mfma_f32_32x32x16_bf16 v[32:47], v[208:211], v[240:243], v[32:47]
	ds_read_b64_tr_b16 v[240:241], v173 offset:9728
	ds_read_b64_tr_b16 v[242:243], v173 offset:11776
	v_exp_f32_e32 v149, v75
	v_exp_f32_e32 v146, v76
	v_exp_f32_e32 v147, v77
	s_waitcnt lgkmcnt(6)
	v_mfma_f32_32x32x16_bf16 v[32:47], v[228:231], v[204:207], v[32:47]
	ds_read_b64_tr_b16 v[204:205], v173 offset:13824
	ds_read_b64_tr_b16 v[206:207], v173 offset:15872
	v_exp_f32_e32 v144, v78
	v_exp_f32_e32 v145, v79
	s_waitcnt vmcnt(4) lgkmcnt(0)
	s_barrier
	ds_read_b128 v[128:131], v179 offset:16384
	ds_read_b128 v[132:135], v179 offset:24576
	ds_read_b128 v[220:223], v182 offset:16384
	ds_read_b128 v[224:227], v182 offset:24576
	v_mfma_f32_32x32x16_bf16 v[48:63], v[136:139], v[232:235], v[48:63]
	s_add_i32 m0, s98, 0xc000
	s_nop 0
	global_load_lds_dwordx4 v216, s[14:15]
	v_mfma_f32_32x32x16_bf16 v[48:63], v[140:143], v[236:239], v[48:63]
	ds_read_b128 v[232:235], v183 offset:16384
	ds_read_b128 v[236:239], v183 offset:24576
	s_add_i32 m0, s98, 0xc400
	s_nop 0
	global_load_lds_dwordx4 v217, s[14:15]
	v_mfma_f32_32x32x16_bf16 v[48:63], v[208:211], v[240:243], v[48:63]
	s_add_i32 m0, s98, 0x0
	s_nop 0
	global_load_lds_dwordx4 v218, s[16:17]
	v_mfma_f32_32x32x16_bf16 v[48:63], v[228:231], v[204:207], v[48:63]
	ds_read_b128 v[240:243], v184 offset:16384
	ds_read_b128 v[204:207], v184 offset:24576
	s_add_i32 m0, s98, 0x400
	s_nop 0
	global_load_lds_dwordx4 v219, s[16:17]
	s_add_u32 s14, s14, 0x10000
	s_addc_u32 s15, s15, 0
	s_add_u32 s16, s16, 0x10000
	s_addc_u32 s17, s17, 0
	s_waitcnt lgkmcnt(7)
	v_mfma_f32_32x32x16_bf16 v[80:95], v[128:131], v[124:127], 0
	v_add_f32_e32 v244, v199, v201
	v_cvt_pk_bf16_f32 v136, v199, v201
	v_add_f32_e32 v244, v198, v244
	v_cvt_pk_bf16_f32 v137, v198, v203
	s_waitcnt lgkmcnt(6)
	v_mfma_f32_32x32x16_bf16 v[64:79], v[132:135], v[124:127], 0
	ds_read_b128 v[128:131], v185 offset:16384
	ds_read_b128 v[132:135], v185 offset:24576
	v_add_f32_e32 v244, v203, v244
	v_cvt_pk_bf16_f32 v138, v200, v202
	v_add_f32_e32 v244, v200, v244
	v_cvt_pk_bf16_f32 v139, v196, v197
	s_waitcnt lgkmcnt(7)
	v_mfma_f32_32x32x16_bf16 v[80:95], v[220:223], v[120:123], v[80:95]
	v_add_f32_e32 v244, v202, v244
	v_cvt_pk_bf16_f32 v140, v193, v195
	v_add_f32_e32 v244, v196, v244
	v_cvt_pk_bf16_f32 v141, v192, v194
	s_waitcnt lgkmcnt(6)
	v_mfma_f32_32x32x16_bf16 v[64:79], v[224:227], v[120:123], v[64:79]
	ds_read_b128 v[220:223], v186 offset:16384
	ds_read_b128 v[224:227], v186 offset:24576
	v_add_f32_e32 v244, v197, v244
	v_cvt_pk_bf16_f32 v142, v189, v191
	v_add_f32_e32 v244, v193, v244
	v_cvt_pk_bf16_f32 v143, v188, v190
	s_waitcnt lgkmcnt(7)
	v_mfma_f32_32x32x16_bf16 v[80:95], v[232:235], v[116:119], v[80:95]
	v_add_f32_e32 v244, v195, v244
	v_cvt_pk_bf16_f32 v208, v168, v169
	v_permlane32_swap_b32_e32 v136, v138
	v_add_f32_e32 v244, v192, v244
	v_cvt_pk_bf16_f32 v209, v166, v167
	s_waitcnt lgkmcnt(6)
	v_mfma_f32_32x32x16_bf16 v[64:79], v[236:239], v[116:119], v[64:79]
	v_add_f32_e32 v244, v194, v244
	v_cvt_pk_bf16_f32 v210, v164, v165
	v_permlane32_swap_b32_e32 v137, v139
	v_add_f32_e32 v244, v189, v244
	v_cvt_pk_bf16_f32 v211, v150, v151
	s_waitcnt lgkmcnt(5)
	v_mfma_f32_32x32x16_bf16 v[80:95], v[240:243], v[112:115], v[80:95]
	v_add_f32_e32 v244, v191, v244
	v_cvt_pk_bf16_f32 v228, v162, v163
	v_permlane32_swap_b32_e32 v140, v142
	v_add_f32_e32 v244, v188, v244
	v_cvt_pk_bf16_f32 v229, v148, v149
	s_waitcnt lgkmcnt(4)
; #define SBAR() __builtin_amdgcn_sched_barrier(0)
; __device__ __forceinline__ void qkt(f32x16& p0, f32x16& p1, const bf16* Ks, const bf16x8* qr, int r32, int hi) {
;   p0 = f32x16{}; p1 = f32x16{};
; #pragma unroll
;   for (int d0 = 0; d0 < 8; ++d0) { int cb = (d0 * 16 + hi * 8) * 2;
;     bf16x8 b0 = *reinterpret_cast<const bf16x8*>((const char*)Ks + KSWZ(r32, cb));
;     bf16x8 b1 = *reinterpret_cast<const bf16x8*>((const char*)Ks + KSWZ(32 + r32, cb));
;     p0 = __builtin_amdgcn_mfma_f32_32x32x16_bf16(b0, qr[d0], p0, 0, 0, 0);
;     p1 = __builtin_amdgcn_mfma_f32_32x32x16_bf16(b1, qr[d0], p1, 0, 0, 0); }
; }
; __device__ __forceinline__ int v_st(int k, int c) { const int kk = (k & ~0xC) | ((k & 4) << 1) | ((k & 8) >> 1); return ((kk >> 3) * 4 + (c >> 5)) * 512 + ((kk & 7) * 32 + (c & 31)) * 2; }
; __device__ __forceinline__ int v_rd_base(int lane) { return ((lane & 3) << 3) | (((lane >> 2) & 3) << 6) | (((lane >> 4) & 1) << 5) | (((lane >> 5) & 1) << 8); }
; template <int OFF> __device__ __forceinline__ s16x4 tr_read(int vb) {
;   s16x4 r; asm volatile("ds_read_b64_tr_b16 %0, %1 offset:%2" : "=&v"(r) : "v"(vb), "i"(OFF) : "memory"); return r;
; }
; template <int D0> __device__ __forceinline__ void pv_one(f32x16& od, int vb, bf16x8 pa0, bf16x8 pa1, bf16x8 pa2, bf16x8 pa3) {
;   const s16x4 l0 = tr_read<v_rd_off(D0, 0, 0)>(vb), h0 = tr_read<v_rd_off(D0, 0, 1)>(vb), l1 = tr_read<v_rd_off(D0, 1, 0)>(vb), h1 = tr_read<v_rd_off(D0, 1, 1)>(vb);
;   const s16x4 l2 = tr_read<v_rd_off(D0, 2, 0)>(vb), h2 = tr_read<v_rd_off(D0, 2, 1)>(vb), l3 = tr_read<v_rd_off(D0, 3, 0)>(vb), h3 = tr_read<v_rd_off(D0, 3, 1)>(vb);
;   asm volatile("s_waitcnt lgkmcnt(0)" ::: "memory"); SBAR();
;     ...
;   od = __builtin_amdgcn_mfma_f32_32x32x16_bf16(pa0, PK(l0, h0), od, 0, 0, 0);
;   od = __builtin_amdgcn_mfma_f32_32x32x16_bf16(pa1, PK(l1, h1), od, 0, 0, 0);
;   od = __builtin_amdgcn_mfma_f32_32x32x16_bf16(pa2, PK(l2, h2), od, 0, 0, 0);
;   od = __builtin_amdgcn_mfma_f32_32x32x16_bf16(pa3, PK(l3, h3), od, 0, 0, 0);
;     ...
; }
; __device__ __forceinline__ void pv_d0(f32x16* o, int vb, bf16x8 pa0, bf16x8 pa1, bf16x8 pa2, bf16x8 pa3) {
;   pv_one<0>(o[0], vb, pa0, pa1, pa2, pa3); pv_one<1>(o[1], vb, pa0, pa1, pa2, pa3); pv_one<2>(o[2], vb, pa0, pa1, pa2, pa3); pv_one<3>(o[3], vb, pa0, pa1, pa2, pa3);
	v_mfma_f32_32x32x16_bf16 v[64:79], v[204:207], v[112:115], v[64:79]
	v_add_f32_e32 v244, v190, v244
	v_cvt_pk_bf16_f32 v230, v146, v147
	v_permlane32_swap_b32_e32 v141, v143
	v_add_f32_e32 v244, v168, v244
	v_cvt_pk_bf16_f32 v231, v144, v145
	s_waitcnt lgkmcnt(3)
	v_mfma_f32_32x32x16_bf16 v[80:95], v[128:131], v[108:111], v[80:95]
	v_add_f32_e32 v244, v169, v244
	v_permlane32_swap_b32_e32 v208, v210
	v_add_f32_e32 v244, v166, v244
	s_waitcnt lgkmcnt(2)
	v_mfma_f32_32x32x16_bf16 v[64:79], v[132:135], v[108:111], v[64:79]
	ds_read_b128 v[128:131], v180 offset:16384
	ds_read_b128 v[132:135], v180 offset:24576
	v_add_f32_e32 v244, v167, v244
	v_permlane32_swap_b32_e32 v209, v211
	v_add_f32_e32 v244, v164, v244
	s_waitcnt lgkmcnt(3)
	v_mfma_f32_32x32x16_bf16 v[80:95], v[220:223], v[104:107], v[80:95]
	v_add_f32_e32 v244, v165, v244
	v_permlane32_swap_b32_e32 v228, v230
	v_add_f32_e32 v244, v150, v244
	s_waitcnt lgkmcnt(2)
	v_mfma_f32_32x32x16_bf16 v[64:79], v[224:227], v[104:107], v[64:79]
	ds_read_b128 v[220:223], v181 offset:16384
	ds_read_b128 v[224:227], v181 offset:24576
	v_add_f32_e32 v244, v151, v244
	v_permlane32_swap_b32_e32 v229, v231
	v_add_f32_e32 v244, v162, v244
	s_waitcnt lgkmcnt(3)
	v_mfma_f32_32x32x16_bf16 v[80:95], v[128:131], v[100:103], v[80:95]
	v_add_f32_e32 v244, v163, v244
	v_add_f32_e32 v244, v148, v244
	ds_read_b64_tr_b16 v[232:233], v153 offset:0
	ds_read_b64_tr_b16 v[234:235], v153 offset:2048
	s_waitcnt lgkmcnt(4)
	v_mfma_f32_32x32x16_bf16 v[64:79], v[132:135], v[100:103], v[64:79]
	v_add_f32_e32 v244, v149, v244
	v_add_f32_e32 v244, v146, v244
	ds_read_b64_tr_b16 v[236:237], v153 offset:4096
	ds_read_b64_tr_b16 v[238:239], v153 offset:6144
	s_waitcnt lgkmcnt(5)
	v_mfma_f32_32x32x16_bf16 v[80:95], v[220:223], v[96:99], v[80:95]
	v_add_f32_e32 v244, v147, v244
	v_add_f32_e32 v244, v144, v244
	ds_read_b64_tr_b16 v[240:241], v153 offset:8192
	ds_read_b64_tr_b16 v[242:243], v153 offset:10240
	s_waitcnt lgkmcnt(6)
	v_mfma_f32_32x32x16_bf16 v[64:79], v[224:227], v[96:99], v[64:79]
	v_add_f32_e32 v244, v145, v244
	v_add_f32_e32 v187, v187, v244
	ds_read_b64_tr_b16 v[204:205], v153 offset:12288
	ds_read_b64_tr_b16 v[206:207], v153 offset:14336
	s_waitcnt lgkmcnt(6)
	v_mfma_f32_32x32x16_bf16 v[0:15], v[136:139], v[232:235], v[0:15]
	ds_read_b64_tr_b16 v[232:233], v153 offset:512
	ds_read_b64_tr_b16 v[234:235], v153 offset:2560
	s_waitcnt lgkmcnt(6)
	v_mfma_f32_32x32x16_bf16 v[0:15], v[140:143], v[236:239], v[0:15]
	ds_read_b64_tr_b16 v[236:237], v153 offset:4608
	ds_read_b64_tr_b16 v[238:239], v153 offset:6656
	v_exp_f32_e32 v199, v80
	v_exp_f32_e32 v201, v81
	v_exp_f32_e32 v198, v82
	s_waitcnt lgkmcnt(6)
	v_mfma_f32_32x32x16_bf16 v[0:15], v[208:211], v[240:243], v[0:15]
	ds_read_b64_tr_b16 v[240:241], v153 offset:8704
	ds_read_b64_tr_b16 v[242:243], v153 offset:10752
	v_exp_f32_e32 v203, v83
	v_exp_f32_e32 v200, v84
	v_exp_f32_e32 v202, v85
	s_waitcnt lgkmcnt(6)
	v_mfma_f32_32x32x16_bf16 v[0:15], v[228:231], v[204:207], v[0:15]
	ds_read_b64_tr_b16 v[204:205], v153 offset:12800
	ds_read_b64_tr_b16 v[206:207], v153 offset:14848
	v_exp_f32_e32 v196, v86
	v_exp_f32_e32 v197, v87
	v_exp_f32_e32 v193, v88
	s_waitcnt lgkmcnt(6)
	v_mfma_f32_32x32x16_bf16 v[16:31], v[136:139], v[232:235], v[16:31]
	ds_read_b64_tr_b16 v[232:233], v153 offset:1024
	ds_read_b64_tr_b16 v[234:235], v153 offset:3072
	v_exp_f32_e32 v195, v89
	v_exp_f32_e32 v192, v90
	v_exp_f32_e32 v194, v91
	s_waitcnt lgkmcnt(6)
	v_mfma_f32_32x32x16_bf16 v[16:31], v[140:143], v[236:239], v[16:31]
	ds_read_b64_tr_b16 v[236:237], v153 offset:5120
	ds_read_b64_tr_b16 v[238:239], v153 offset:7168
	v_exp_f32_e32 v189, v92
	v_exp_f32_e32 v191, v93
	v_exp_f32_e32 v188, v94
	s_waitcnt lgkmcnt(6)
	v_mfma_f32_32x32x16_bf16 v[16:31], v[208:211], v[240:243], v[16:31]
	ds_read_b64_tr_b16 v[240:241], v153 offset:9216
	ds_read_b64_tr_b16 v[242:243], v153 offset:11264
	v_exp_f32_e32 v190, v95
	v_exp_f32_e32 v168, v64
	v_exp_f32_e32 v169, v65
	s_waitcnt lgkmcnt(6)
	v_mfma_f32_32x32x16_bf16 v[16:31], v[228:231], v[204:207], v[16:31]
	ds_read_b64_tr_b16 v[204:205], v153 offset:13312
	ds_read_b64_tr_b16 v[206:207], v153 offset:15360
	v_exp_f32_e32 v166, v66
	v_exp_f32_e32 v167, v67
	v_exp_f32_e32 v164, v68
	s_waitcnt lgkmcnt(6)
	v_mfma_f32_32x32x16_bf16 v[32:47], v[136:139], v[232:235], v[32:47]
	ds_read_b64_tr_b16 v[232:233], v153 offset:1536
	ds_read_b64_tr_b16 v[234:235], v153 offset:3584
	v_exp_f32_e32 v165, v69
	v_exp_f32_e32 v150, v70
	v_exp_f32_e32 v151, v71
	s_waitcnt lgkmcnt(6)
	v_mfma_f32_32x32x16_bf16 v[32:47], v[140:143], v[236:239], v[32:47]
	ds_read_b64_tr_b16 v[236:237], v153 offset:5632
	ds_read_b64_tr_b16 v[238:239], v153 offset:7680
	v_exp_f32_e32 v162, v72
	v_exp_f32_e32 v163, v73
	v_exp_f32_e32 v148, v74
	s_waitcnt lgkmcnt(6)
	v_mfma_f32_32x32x16_bf16 v[32:47], v[208:211], v[240:243], v[32:47]
	ds_read_b64_tr_b16 v[240:241], v153 offset:9728
	ds_read_b64_tr_b16 v[242:243], v153 offset:11776
	v_exp_f32_e32 v149, v75
	v_exp_f32_e32 v146, v76
	v_exp_f32_e32 v147, v77
	s_waitcnt lgkmcnt(6)
	v_mfma_f32_32x32x16_bf16 v[32:47], v[228:231], v[204:207], v[32:47]
	ds_read_b64_tr_b16 v[204:205], v153 offset:13824
	ds_read_b64_tr_b16 v[206:207], v153 offset:15872
	v_exp_f32_e32 v144, v78
	v_exp_f32_e32 v145, v79
	s_waitcnt vmcnt(4) lgkmcnt(0)
	s_barrier
; #define SBAR() __builtin_amdgcn_sched_barrier(0)
; __device__ __forceinline__ void qkt(f32x16& p0, f32x16& p1, const bf16* Ks, const bf16x8* qr, int r32, int hi) {
;   p0 = f32x16{}; p1 = f32x16{};
; #pragma unroll
;   for (int d0 = 0; d0 < 8; ++d0) { int cb = (d0 * 16 + hi * 8) * 2;
;     bf16x8 b0 = *reinterpret_cast<const bf16x8*>((const char*)Ks + KSWZ(r32, cb));
;     bf16x8 b1 = *reinterpret_cast<const bf16x8*>((const char*)Ks + KSWZ(32 + r32, cb));
;     p0 = __builtin_amdgcn_mfma_f32_32x32x16_bf16(b0, qr[d0], p0, 0, 0, 0);
;     p1 = __builtin_amdgcn_mfma_f32_32x32x16_bf16(b1, qr[d0], p1, 0, 0, 0); }
; }
; __device__ __forceinline__ int v_st(int k, int c) { const int kk = (k & ~0xC) | ((k & 4) << 1) | ((k & 8) >> 1); return ((kk >> 3) * 4 + (c >> 5)) * 512 + ((kk & 7) * 32 + (c & 31)) * 2; }
; __device__ __forceinline__ int v_rd_base(int lane) { return ((lane & 3) << 3) | (((lane >> 2) & 3) << 6) | (((lane >> 4) & 1) << 5) | (((lane >> 5) & 1) << 8); }
; template <int OFF> __device__ __forceinline__ s16x4 tr_read(int vb) {
;   s16x4 r; asm volatile("ds_read_b64_tr_b16 %0, %1 offset:%2" : "=&v"(r) : "v"(vb), "i"(OFF) : "memory"); return r;
; }
; template <int D0> __device__ __forceinline__ void pv_one(f32x16& od, int vb, bf16x8 pa0, bf16x8 pa1, bf16x8 pa2, bf16x8 pa3) {
;   const s16x4 l0 = tr_read<v_rd_off(D0, 0, 0)>(vb), h0 = tr_read<v_rd_off(D0, 0, 1)>(vb), l1 = tr_read<v_rd_off(D0, 1, 0)>(vb), h1 = tr_read<v_rd_off(D0, 1, 1)>(vb);
;   const s16x4 l2 = tr_read<v_rd_off(D0, 2, 0)>(vb), h2 = tr_read<v_rd_off(D0, 2, 1)>(vb), l3 = tr_read<v_rd_off(D0, 3, 0)>(vb), h3 = tr_read<v_rd_off(D0, 3, 1)>(vb);
;   asm volatile("s_waitcnt lgkmcnt(0)" ::: "memory"); SBAR();
;     ...
;   od = __builtin_amdgcn_mfma_f32_32x32x16_bf16(pa0, PK(l0, h0), od, 0, 0, 0);
;   od = __builtin_amdgcn_mfma_f32_32x32x16_bf16(pa1, PK(l1, h1), od, 0, 0, 0);
;   od = __builtin_amdgcn_mfma_f32_32x32x16_bf16(pa2, PK(l2, h2), od, 0, 0, 0);
;   od = __builtin_amdgcn_mfma_f32_32x32x16_bf16(pa3, PK(l3, h3), od, 0, 0, 0);
;     ...
; }
; __device__ __forceinline__ void pv_d0(f32x16* o, int vb, bf16x8 pa0, bf16x8 pa1, bf16x8 pa2, bf16x8 pa3) {
;   pv_one<0>(o[0], vb, pa0, pa1, pa2, pa3); pv_one<1>(o[1], vb, pa0, pa1, pa2, pa3); pv_one<2>(o[2], vb, pa0, pa1, pa2, pa3); pv_one<3>(o[3], vb, pa0, pa1, pa2, pa3);
	ds_read_b128 v[128:131], v179 offset:32768
	ds_read_b128 v[132:135], v179 offset:40960
	ds_read_b128 v[220:223], v182 offset:32768
	ds_read_b128 v[224:227], v182 offset:40960
	v_mfma_f32_32x32x16_bf16 v[48:63], v[136:139], v[232:235], v[48:63]
	s_add_i32 m0, s98, 0x4000
	s_nop 0
	global_load_lds_dwordx4 v216, s[14:15]
	v_mfma_f32_32x32x16_bf16 v[48:63], v[140:143], v[236:239], v[48:63]
	ds_read_b128 v[232:235], v183 offset:32768
	ds_read_b128 v[236:239], v183 offset:40960
	s_add_i32 m0, s98, 0x4400
	s_nop 0
	global_load_lds_dwordx4 v217, s[14:15]
	v_mfma_f32_32x32x16_bf16 v[48:63], v[208:211], v[240:243], v[48:63]
	s_add_i32 m0, s98, 0x10000
	s_nop 0
	global_load_lds_dwordx4 v218, s[16:17]
	v_mfma_f32_32x32x16_bf16 v[48:63], v[228:231], v[204:207], v[48:63]
	ds_read_b128 v[240:243], v184 offset:32768
	ds_read_b128 v[204:207], v184 offset:40960
	s_add_i32 m0, s98, 0x10400
	s_nop 0
	global_load_lds_dwordx4 v219, s[16:17]
	s_add_u32 s14, s14, 0x10000
	s_addc_u32 s15, s15, 0
	s_add_u32 s16, s16, 0x10000
	s_addc_u32 s17, s17, 0
	s_waitcnt lgkmcnt(7)
	v_mfma_f32_32x32x16_bf16 v[80:95], v[128:131], v[124:127], 0
	v_add_f32_e32 v244, v199, v201
	v_cvt_pk_bf16_f32 v136, v199, v201
	v_add_f32_e32 v244, v198, v244
	v_cvt_pk_bf16_f32 v137, v198, v203
	s_waitcnt lgkmcnt(6)
	v_mfma_f32_32x32x16_bf16 v[64:79], v[132:135], v[124:127], 0
	ds_read_b128 v[128:131], v185 offset:32768
	ds_read_b128 v[132:135], v185 offset:40960
	v_add_f32_e32 v244, v203, v244
	v_cvt_pk_bf16_f32 v138, v200, v202
	v_add_f32_e32 v244, v200, v244
	v_cvt_pk_bf16_f32 v139, v196, v197
	s_waitcnt lgkmcnt(7)
	v_mfma_f32_32x32x16_bf16 v[80:95], v[220:223], v[120:123], v[80:95]
	v_add_f32_e32 v244, v202, v244
	v_cvt_pk_bf16_f32 v140, v193, v195
	v_add_f32_e32 v244, v196, v244
	v_cvt_pk_bf16_f32 v141, v192, v194
	s_waitcnt lgkmcnt(6)
	v_mfma_f32_32x32x16_bf16 v[64:79], v[224:227], v[120:123], v[64:79]
	ds_read_b128 v[220:223], v186 offset:32768
	ds_read_b128 v[224:227], v186 offset:40960
	v_add_f32_e32 v244, v197, v244
	v_cvt_pk_bf16_f32 v142, v189, v191
	v_add_f32_e32 v244, v193, v244
	v_cvt_pk_bf16_f32 v143, v188, v190
	s_waitcnt lgkmcnt(7)
	v_mfma_f32_32x32x16_bf16 v[80:95], v[232:235], v[116:119], v[80:95]
	v_add_f32_e32 v244, v195, v244
	v_cvt_pk_bf16_f32 v208, v168, v169
	v_permlane32_swap_b32_e32 v136, v138
	v_add_f32_e32 v244, v192, v244
	v_cvt_pk_bf16_f32 v209, v166, v167
	s_waitcnt lgkmcnt(6)
	v_mfma_f32_32x32x16_bf16 v[64:79], v[236:239], v[116:119], v[64:79]
	v_add_f32_e32 v244, v194, v244
	v_cvt_pk_bf16_f32 v210, v164, v165
	v_permlane32_swap_b32_e32 v137, v139
	v_add_f32_e32 v244, v189, v244
	v_cvt_pk_bf16_f32 v211, v150, v151
	s_waitcnt lgkmcnt(5)
	v_mfma_f32_32x32x16_bf16 v[80:95], v[240:243], v[112:115], v[80:95]
	v_add_f32_e32 v244, v191, v244
	v_cvt_pk_bf16_f32 v228, v162, v163
	v_permlane32_swap_b32_e32 v140, v142
	v_add_f32_e32 v244, v188, v244
	v_cvt_pk_bf16_f32 v229, v148, v149
	s_waitcnt lgkmcnt(4)
	v_mfma_f32_32x32x16_bf16 v[64:79], v[204:207], v[112:115], v[64:79]
	v_add_f32_e32 v244, v190, v244
	v_cvt_pk_bf16_f32 v230, v146, v147
	v_permlane32_swap_b32_e32 v141, v143
	v_add_f32_e32 v244, v168, v244
	v_cvt_pk_bf16_f32 v231, v144, v145
	s_waitcnt lgkmcnt(3)
	v_mfma_f32_32x32x16_bf16 v[80:95], v[128:131], v[108:111], v[80:95]
	v_add_f32_e32 v244, v169, v244
	v_permlane32_swap_b32_e32 v208, v210
	v_add_f32_e32 v244, v166, v244
	s_waitcnt lgkmcnt(2)
	v_mfma_f32_32x32x16_bf16 v[64:79], v[132:135], v[108:111], v[64:79]
	ds_read_b128 v[128:131], v180 offset:32768
	ds_read_b128 v[132:135], v180 offset:40960
	v_add_f32_e32 v244, v167, v244
	v_permlane32_swap_b32_e32 v209, v211
	v_add_f32_e32 v244, v164, v244
	s_waitcnt lgkmcnt(3)
	v_mfma_f32_32x32x16_bf16 v[80:95], v[220:223], v[104:107], v[80:95]
	v_add_f32_e32 v244, v165, v244
	v_permlane32_swap_b32_e32 v228, v230
	v_add_f32_e32 v244, v150, v244
	s_waitcnt lgkmcnt(2)
	v_mfma_f32_32x32x16_bf16 v[64:79], v[224:227], v[104:107], v[64:79]
	ds_read_b128 v[220:223], v181 offset:32768
	ds_read_b128 v[224:227], v181 offset:40960
	v_add_f32_e32 v244, v151, v244
	v_permlane32_swap_b32_e32 v229, v231
	v_add_f32_e32 v244, v162, v244
	s_waitcnt lgkmcnt(3)
	v_mfma_f32_32x32x16_bf16 v[80:95], v[128:131], v[100:103], v[80:95]
	v_add_f32_e32 v244, v163, v244
	v_add_f32_e32 v244, v148, v244
	ds_read_b64_tr_b16 v[232:233], v153 offset:16384
	ds_read_b64_tr_b16 v[234:235], v153 offset:18432
	s_waitcnt lgkmcnt(4)
	v_mfma_f32_32x32x16_bf16 v[64:79], v[132:135], v[100:103], v[64:79]
	v_add_f32_e32 v244, v149, v244
	v_add_f32_e32 v244, v146, v244
	ds_read_b64_tr_b16 v[236:237], v153 offset:20480
	ds_read_b64_tr_b16 v[238:239], v153 offset:22528
	s_waitcnt lgkmcnt(5)
	v_mfma_f32_32x32x16_bf16 v[80:95], v[220:223], v[96:99], v[80:95]
	v_add_f32_e32 v244, v147, v244
	v_add_f32_e32 v244, v144, v244
	ds_read_b64_tr_b16 v[240:241], v153 offset:24576
	ds_read_b64_tr_b16 v[242:243], v153 offset:26624
	s_waitcnt lgkmcnt(6)
	v_mfma_f32_32x32x16_bf16 v[64:79], v[224:227], v[96:99], v[64:79]
	v_add_f32_e32 v244, v145, v244
	v_add_f32_e32 v187, v187, v244
	ds_read_b64_tr_b16 v[204:205], v153 offset:28672
	ds_read_b64_tr_b16 v[206:207], v153 offset:30720
	s_waitcnt lgkmcnt(6)
	v_mfma_f32_32x32x16_bf16 v[0:15], v[136:139], v[232:235], v[0:15]
	ds_read_b64_tr_b16 v[232:233], v153 offset:16896
	ds_read_b64_tr_b16 v[234:235], v153 offset:18944
	s_waitcnt lgkmcnt(6)
	v_mfma_f32_32x32x16_bf16 v[0:15], v[140:143], v[236:239], v[0:15]
	ds_read_b64_tr_b16 v[236:237], v153 offset:20992
	ds_read_b64_tr_b16 v[238:239], v153 offset:23040
	v_exp_f32_e32 v199, v80
	v_exp_f32_e32 v201, v81
	v_exp_f32_e32 v198, v82
	s_waitcnt lgkmcnt(6)
; #define SBAR() __builtin_amdgcn_sched_barrier(0)
; __device__ __forceinline__ void qkt(f32x16& p0, f32x16& p1, const bf16* Ks, const bf16x8* qr, int r32, int hi) {
;   p0 = f32x16{}; p1 = f32x16{};
; #pragma unroll
;   for (int d0 = 0; d0 < 8; ++d0) { int cb = (d0 * 16 + hi * 8) * 2;
;     bf16x8 b0 = *reinterpret_cast<const bf16x8*>((const char*)Ks + KSWZ(r32, cb));
;     bf16x8 b1 = *reinterpret_cast<const bf16x8*>((const char*)Ks + KSWZ(32 + r32, cb));
;     p0 = __builtin_amdgcn_mfma_f32_32x32x16_bf16(b0, qr[d0], p0, 0, 0, 0);
;     p1 = __builtin_amdgcn_mfma_f32_32x32x16_bf16(b1, qr[d0], p1, 0, 0, 0); }
; }
; __device__ __forceinline__ int v_st(int k, int c) { const int kk = (k & ~0xC) | ((k & 4) << 1) | ((k & 8) >> 1); return ((kk >> 3) * 4 + (c >> 5)) * 512 + ((kk & 7) * 32 + (c & 31)) * 2; }
; __device__ __forceinline__ int v_rd_base(int lane) { return ((lane & 3) << 3) | (((lane >> 2) & 3) << 6) | (((lane >> 4) & 1) << 5) | (((lane >> 5) & 1) << 8); }
; template <int OFF> __device__ __forceinline__ s16x4 tr_read(int vb) {
;   s16x4 r; asm volatile("ds_read_b64_tr_b16 %0, %1 offset:%2" : "=&v"(r) : "v"(vb), "i"(OFF) : "memory"); return r;
; }
; template <int D0> __device__ __forceinline__ void pv_one(f32x16& od, int vb, bf16x8 pa0, bf16x8 pa1, bf16x8 pa2, bf16x8 pa3) {
;   const s16x4 l0 = tr_read<v_rd_off(D0, 0, 0)>(vb), h0 = tr_read<v_rd_off(D0, 0, 1)>(vb), l1 = tr_read<v_rd_off(D0, 1, 0)>(vb), h1 = tr_read<v_rd_off(D0, 1, 1)>(vb);
;   const s16x4 l2 = tr_read<v_rd_off(D0, 2, 0)>(vb), h2 = tr_read<v_rd_off(D0, 2, 1)>(vb), l3 = tr_read<v_rd_off(D0, 3, 0)>(vb), h3 = tr_read<v_rd_off(D0, 3, 1)>(vb);
;   asm volatile("s_waitcnt lgkmcnt(0)" ::: "memory"); SBAR();
;     ...
;   od = __builtin_amdgcn_mfma_f32_32x32x16_bf16(pa0, PK(l0, h0), od, 0, 0, 0);
;   od = __builtin_amdgcn_mfma_f32_32x32x16_bf16(pa1, PK(l1, h1), od, 0, 0, 0);
;   od = __builtin_amdgcn_mfma_f32_32x32x16_bf16(pa2, PK(l2, h2), od, 0, 0, 0);
;   od = __builtin_amdgcn_mfma_f32_32x32x16_bf16(pa3, PK(l3, h3), od, 0, 0, 0);
;     ...
; }
; __device__ __forceinline__ void pv_d0(f32x16* o, int vb, bf16x8 pa0, bf16x8 pa1, bf16x8 pa2, bf16x8 pa3) {
;   pv_one<0>(o[0], vb, pa0, pa1, pa2, pa3); pv_one<1>(o[1], vb, pa0, pa1, pa2, pa3); pv_one<2>(o[2], vb, pa0, pa1, pa2, pa3); pv_one<3>(o[3], vb, pa0, pa1, pa2, pa3);
	v_mfma_f32_32x32x16_bf16 v[0:15], v[208:211], v[240:243], v[0:15]
	ds_read_b64_tr_b16 v[240:241], v153 offset:25088
	ds_read_b64_tr_b16 v[242:243], v153 offset:27136
	v_exp_f32_e32 v203, v83
	v_exp_f32_e32 v200, v84
	v_exp_f32_e32 v202, v85
	s_waitcnt lgkmcnt(6)
	v_mfma_f32_32x32x16_bf16 v[0:15], v[228:231], v[204:207], v[0:15]
	ds_read_b64_tr_b16 v[204:205], v153 offset:29184
	ds_read_b64_tr_b16 v[206:207], v153 offset:31232
	v_exp_f32_e32 v196, v86
	v_exp_f32_e32 v197, v87
	v_exp_f32_e32 v193, v88
	s_waitcnt lgkmcnt(6)
	v_mfma_f32_32x32x16_bf16 v[16:31], v[136:139], v[232:235], v[16:31]
	ds_read_b64_tr_b16 v[232:233], v153 offset:17408
	ds_read_b64_tr_b16 v[234:235], v153 offset:19456
	v_exp_f32_e32 v195, v89
	v_exp_f32_e32 v192, v90
	v_exp_f32_e32 v194, v91
	s_waitcnt lgkmcnt(6)
	v_mfma_f32_32x32x16_bf16 v[16:31], v[140:143], v[236:239], v[16:31]
	ds_read_b64_tr_b16 v[236:237], v153 offset:21504
	ds_read_b64_tr_b16 v[238:239], v153 offset:23552
	v_exp_f32_e32 v189, v92
	v_exp_f32_e32 v191, v93
	v_exp_f32_e32 v188, v94
	s_waitcnt lgkmcnt(6)
	v_mfma_f32_32x32x16_bf16 v[16:31], v[208:211], v[240:243], v[16:31]
	ds_read_b64_tr_b16 v[240:241], v153 offset:25600
	ds_read_b64_tr_b16 v[242:243], v153 offset:27648
	v_exp_f32_e32 v190, v95
	v_exp_f32_e32 v168, v64
	v_exp_f32_e32 v169, v65
	s_waitcnt lgkmcnt(6)
	v_mfma_f32_32x32x16_bf16 v[16:31], v[228:231], v[204:207], v[16:31]
	ds_read_b64_tr_b16 v[204:205], v153 offset:29696
	ds_read_b64_tr_b16 v[206:207], v153 offset:31744
	v_exp_f32_e32 v166, v66
	v_exp_f32_e32 v167, v67
	v_exp_f32_e32 v164, v68
	s_waitcnt lgkmcnt(6)
	v_mfma_f32_32x32x16_bf16 v[32:47], v[136:139], v[232:235], v[32:47]
	ds_read_b64_tr_b16 v[232:233], v153 offset:17920
	ds_read_b64_tr_b16 v[234:235], v153 offset:19968
	v_exp_f32_e32 v165, v69
	v_exp_f32_e32 v150, v70
	v_exp_f32_e32 v151, v71
	s_waitcnt lgkmcnt(6)
	v_mfma_f32_32x32x16_bf16 v[32:47], v[140:143], v[236:239], v[32:47]
	ds_read_b64_tr_b16 v[236:237], v153 offset:22016
	ds_read_b64_tr_b16 v[238:239], v153 offset:24064
	v_exp_f32_e32 v162, v72
	v_exp_f32_e32 v163, v73
	v_exp_f32_e32 v148, v74
	s_waitcnt lgkmcnt(6)
	v_mfma_f32_32x32x16_bf16 v[32:47], v[208:211], v[240:243], v[32:47]
	ds_read_b64_tr_b16 v[240:241], v153 offset:26112
	ds_read_b64_tr_b16 v[242:243], v153 offset:28160
	v_exp_f32_e32 v149, v75
	v_exp_f32_e32 v146, v76
	v_exp_f32_e32 v147, v77
	s_waitcnt lgkmcnt(6)
	v_mfma_f32_32x32x16_bf16 v[32:47], v[228:231], v[204:207], v[32:47]
	ds_read_b64_tr_b16 v[204:205], v153 offset:30208
	ds_read_b64_tr_b16 v[206:207], v153 offset:32256
	v_exp_f32_e32 v144, v78
	v_exp_f32_e32 v145, v79
	s_sub_i32 s12, s12, 1
	s_cmp_lg_u32 s12, 0
	s_waitcnt vmcnt(4) lgkmcnt(0)
	s_barrier
	s_cbranch_scc1 .LBB0_1040
	ds_read_b128 v[128:131], v179 offset:49152
	ds_read_b128 v[132:135], v179 offset:57344
	ds_read_b128 v[220:223], v182 offset:49152
	ds_read_b128 v[224:227], v182 offset:57344
	v_mfma_f32_32x32x16_bf16 v[48:63], v[136:139], v[232:235], v[48:63]
	v_mfma_f32_32x32x16_bf16 v[48:63], v[140:143], v[236:239], v[48:63]
	ds_read_b128 v[232:235], v183 offset:49152
	ds_read_b128 v[236:239], v183 offset:57344
	v_mfma_f32_32x32x16_bf16 v[48:63], v[208:211], v[240:243], v[48:63]
	s_add_i32 m0, s98, 0x14000
	s_nop 0
	global_load_lds_dwordx4 v218, s[16:17]
	v_mfma_f32_32x32x16_bf16 v[48:63], v[228:231], v[204:207], v[48:63]
	ds_read_b128 v[240:243], v184 offset:49152
	ds_read_b128 v[204:207], v184 offset:57344
	s_add_i32 m0, s98, 0x14400
	s_nop 0
	global_load_lds_dwordx4 v219, s[16:17]
	s_add_u32 s14, s14, 0x10000
	s_addc_u32 s15, s15, 0
	s_add_u32 s16, s16, 0x10000
	s_addc_u32 s17, s17, 0
	s_waitcnt lgkmcnt(7)
	v_mfma_f32_32x32x16_bf16 v[80:95], v[128:131], v[124:127], 0
	v_add_f32_e32 v244, v199, v201
	v_cvt_pk_bf16_f32 v136, v199, v201
	v_add_f32_e32 v244, v198, v244
	v_cvt_pk_bf16_f32 v137, v198, v203
	s_waitcnt lgkmcnt(6)
	v_mfma_f32_32x32x16_bf16 v[64:79], v[132:135], v[124:127], 0
	ds_read_b128 v[128:131], v185 offset:49152
	ds_read_b128 v[132:135], v185 offset:57344
	v_add_f32_e32 v244, v203, v244
	v_cvt_pk_bf16_f32 v138, v200, v202
	v_add_f32_e32 v244, v200, v244
	v_cvt_pk_bf16_f32 v139, v196, v197
	s_waitcnt lgkmcnt(7)
	v_mfma_f32_32x32x16_bf16 v[80:95], v[220:223], v[120:123], v[80:95]
	v_add_f32_e32 v244, v202, v244
	v_cvt_pk_bf16_f32 v140, v193, v195
	v_add_f32_e32 v244, v196, v244
	v_cvt_pk_bf16_f32 v141, v192, v194
	s_waitcnt lgkmcnt(6)
	v_mfma_f32_32x32x16_bf16 v[64:79], v[224:227], v[120:123], v[64:79]
	ds_read_b128 v[220:223], v186 offset:49152
	ds_read_b128 v[224:227], v186 offset:57344
	v_add_f32_e32 v244, v197, v244
	v_cvt_pk_bf16_f32 v142, v189, v191
	v_add_f32_e32 v244, v193, v244
	v_cvt_pk_bf16_f32 v143, v188, v190
	s_waitcnt lgkmcnt(7)
	v_mfma_f32_32x32x16_bf16 v[80:95], v[232:235], v[116:119], v[80:95]
	v_add_f32_e32 v244, v195, v244
	v_cvt_pk_bf16_f32 v208, v168, v169
	v_permlane32_swap_b32_e32 v136, v138
	v_add_f32_e32 v244, v192, v244
	v_cvt_pk_bf16_f32 v209, v166, v167
	s_waitcnt lgkmcnt(6)
	v_mfma_f32_32x32x16_bf16 v[64:79], v[236:239], v[116:119], v[64:79]
	v_add_f32_e32 v244, v194, v244
	v_cvt_pk_bf16_f32 v210, v164, v165
	v_permlane32_swap_b32_e32 v137, v139
	v_add_f32_e32 v244, v189, v244
	v_cvt_pk_bf16_f32 v211, v150, v151
	s_waitcnt lgkmcnt(5)
	v_mfma_f32_32x32x16_bf16 v[80:95], v[240:243], v[112:115], v[80:95]
	v_add_f32_e32 v244, v191, v244
	v_cvt_pk_bf16_f32 v228, v162, v163
	v_permlane32_swap_b32_e32 v140, v142
	v_add_f32_e32 v244, v188, v244
	v_cvt_pk_bf16_f32 v229, v148, v149
	s_waitcnt lgkmcnt(4)
	v_mfma_f32_32x32x16_bf16 v[64:79], v[204:207], v[112:115], v[64:79]
	v_add_f32_e32 v244, v190, v244
	v_cvt_pk_bf16_f32 v230, v146, v147
	v_permlane32_swap_b32_e32 v141, v143
	v_add_f32_e32 v244, v168, v244
	v_cvt_pk_bf16_f32 v231, v144, v145
	s_waitcnt lgkmcnt(3)
; #define SBAR() __builtin_amdgcn_sched_barrier(0)
; __device__ __forceinline__ void qkt(f32x16& p0, f32x16& p1, const bf16* Ks, const bf16x8* qr, int r32, int hi) {
;   p0 = f32x16{}; p1 = f32x16{};
; #pragma unroll
;   for (int d0 = 0; d0 < 8; ++d0) { int cb = (d0 * 16 + hi * 8) * 2;
;     bf16x8 b0 = *reinterpret_cast<const bf16x8*>((const char*)Ks + KSWZ(r32, cb));
;     bf16x8 b1 = *reinterpret_cast<const bf16x8*>((const char*)Ks + KSWZ(32 + r32, cb));
;     p0 = __builtin_amdgcn_mfma_f32_32x32x16_bf16(b0, qr[d0], p0, 0, 0, 0);
;     p1 = __builtin_amdgcn_mfma_f32_32x32x16_bf16(b1, qr[d0], p1, 0, 0, 0); }
; }
; __device__ __forceinline__ int v_st(int k, int c) { const int kk = (k & ~0xC) | ((k & 4) << 1) | ((k & 8) >> 1); return ((kk >> 3) * 4 + (c >> 5)) * 512 + ((kk & 7) * 32 + (c & 31)) * 2; }
; __device__ __forceinline__ int v_rd_base(int lane) { return ((lane & 3) << 3) | (((lane >> 2) & 3) << 6) | (((lane >> 4) & 1) << 5) | (((lane >> 5) & 1) << 8); }
; template <int OFF> __device__ __forceinline__ s16x4 tr_read(int vb) {
;   s16x4 r; asm volatile("ds_read_b64_tr_b16 %0, %1 offset:%2" : "=&v"(r) : "v"(vb), "i"(OFF) : "memory"); return r;
; }
; template <int D0> __device__ __forceinline__ void pv_one(f32x16& od, int vb, bf16x8 pa0, bf16x8 pa1, bf16x8 pa2, bf16x8 pa3) {
;   const s16x4 l0 = tr_read<v_rd_off(D0, 0, 0)>(vb), h0 = tr_read<v_rd_off(D0, 0, 1)>(vb), l1 = tr_read<v_rd_off(D0, 1, 0)>(vb), h1 = tr_read<v_rd_off(D0, 1, 1)>(vb);
;   const s16x4 l2 = tr_read<v_rd_off(D0, 2, 0)>(vb), h2 = tr_read<v_rd_off(D0, 2, 1)>(vb), l3 = tr_read<v_rd_off(D0, 3, 0)>(vb), h3 = tr_read<v_rd_off(D0, 3, 1)>(vb);
;   asm volatile("s_waitcnt lgkmcnt(0)" ::: "memory"); SBAR();
;     ...
;   od = __builtin_amdgcn_mfma_f32_32x32x16_bf16(pa0, PK(l0, h0), od, 0, 0, 0);
;   od = __builtin_amdgcn_mfma_f32_32x32x16_bf16(pa1, PK(l1, h1), od, 0, 0, 0);
;   od = __builtin_amdgcn_mfma_f32_32x32x16_bf16(pa2, PK(l2, h2), od, 0, 0, 0);
;   od = __builtin_amdgcn_mfma_f32_32x32x16_bf16(pa3, PK(l3, h3), od, 0, 0, 0);
;     ...
; }
; __device__ __forceinline__ void pv_d0(f32x16* o, int vb, bf16x8 pa0, bf16x8 pa1, bf16x8 pa2, bf16x8 pa3) {
;   pv_one<0>(o[0], vb, pa0, pa1, pa2, pa3); pv_one<1>(o[1], vb, pa0, pa1, pa2, pa3); pv_one<2>(o[2], vb, pa0, pa1, pa2, pa3); pv_one<3>(o[3], vb, pa0, pa1, pa2, pa3);
	v_mfma_f32_32x32x16_bf16 v[80:95], v[128:131], v[108:111], v[80:95]
	v_add_f32_e32 v244, v169, v244
	v_permlane32_swap_b32_e32 v208, v210
	v_add_f32_e32 v244, v166, v244
	s_waitcnt lgkmcnt(2)
	v_mfma_f32_32x32x16_bf16 v[64:79], v[132:135], v[108:111], v[64:79]
	ds_read_b128 v[128:131], v180 offset:49152
	ds_read_b128 v[132:135], v180 offset:57344
	v_add_f32_e32 v244, v167, v244
	v_permlane32_swap_b32_e32 v209, v211
	v_add_f32_e32 v244, v164, v244
	s_waitcnt lgkmcnt(3)
	v_mfma_f32_32x32x16_bf16 v[80:95], v[220:223], v[104:107], v[80:95]
	v_add_f32_e32 v244, v165, v244
	v_permlane32_swap_b32_e32 v228, v230
	v_add_f32_e32 v244, v150, v244
	s_waitcnt lgkmcnt(2)
	v_mfma_f32_32x32x16_bf16 v[64:79], v[224:227], v[104:107], v[64:79]
	ds_read_b128 v[220:223], v181 offset:49152
	ds_read_b128 v[224:227], v181 offset:57344
	v_add_f32_e32 v244, v151, v244
	v_permlane32_swap_b32_e32 v229, v231
	v_add_f32_e32 v244, v162, v244
	s_waitcnt lgkmcnt(3)
	v_mfma_f32_32x32x16_bf16 v[80:95], v[128:131], v[100:103], v[80:95]
	v_add_f32_e32 v244, v163, v244
	v_add_f32_e32 v244, v148, v244
	ds_read_b64_tr_b16 v[232:233], v173 offset:0
	ds_read_b64_tr_b16 v[234:235], v173 offset:2048
	s_waitcnt lgkmcnt(4)
	v_mfma_f32_32x32x16_bf16 v[64:79], v[132:135], v[100:103], v[64:79]
	v_add_f32_e32 v244, v149, v244
	v_add_f32_e32 v244, v146, v244
	ds_read_b64_tr_b16 v[236:237], v173 offset:4096
	ds_read_b64_tr_b16 v[238:239], v173 offset:6144
	s_waitcnt lgkmcnt(5)
	v_mfma_f32_32x32x16_bf16 v[80:95], v[220:223], v[96:99], v[80:95]
	v_add_f32_e32 v244, v147, v244
	v_add_f32_e32 v244, v144, v244
	ds_read_b64_tr_b16 v[240:241], v173 offset:8192
	ds_read_b64_tr_b16 v[242:243], v173 offset:10240
	s_waitcnt lgkmcnt(6)
	v_mfma_f32_32x32x16_bf16 v[64:79], v[224:227], v[96:99], v[64:79]
	v_add_f32_e32 v244, v145, v244
	v_add_f32_e32 v187, v187, v244
	ds_read_b64_tr_b16 v[204:205], v173 offset:12288
	ds_read_b64_tr_b16 v[206:207], v173 offset:14336
	s_waitcnt lgkmcnt(6)
	v_mfma_f32_32x32x16_bf16 v[0:15], v[136:139], v[232:235], v[0:15]
	ds_read_b64_tr_b16 v[232:233], v173 offset:512
	ds_read_b64_tr_b16 v[234:235], v173 offset:2560
	s_waitcnt lgkmcnt(6)
	v_mfma_f32_32x32x16_bf16 v[0:15], v[140:143], v[236:239], v[0:15]
	ds_read_b64_tr_b16 v[236:237], v173 offset:4608
	ds_read_b64_tr_b16 v[238:239], v173 offset:6656
	v_exp_f32_e32 v199, v80
	v_exp_f32_e32 v201, v81
	v_exp_f32_e32 v198, v82
	s_waitcnt lgkmcnt(6)
	v_mfma_f32_32x32x16_bf16 v[0:15], v[208:211], v[240:243], v[0:15]
	ds_read_b64_tr_b16 v[240:241], v173 offset:8704
	ds_read_b64_tr_b16 v[242:243], v173 offset:10752
	v_exp_f32_e32 v203, v83
	v_exp_f32_e32 v200, v84
	v_exp_f32_e32 v202, v85
	s_waitcnt lgkmcnt(6)
	v_mfma_f32_32x32x16_bf16 v[0:15], v[228:231], v[204:207], v[0:15]
	ds_read_b64_tr_b16 v[204:205], v173 offset:12800
	ds_read_b64_tr_b16 v[206:207], v173 offset:14848
	v_exp_f32_e32 v196, v86
	v_exp_f32_e32 v197, v87
	v_exp_f32_e32 v193, v88
	s_waitcnt lgkmcnt(6)
	v_mfma_f32_32x32x16_bf16 v[16:31], v[136:139], v[232:235], v[16:31]
	ds_read_b64_tr_b16 v[232:233], v173 offset:1024
	ds_read_b64_tr_b16 v[234:235], v173 offset:3072
	v_exp_f32_e32 v195, v89
	v_exp_f32_e32 v192, v90
	v_exp_f32_e32 v194, v91
	s_waitcnt lgkmcnt(6)
	v_mfma_f32_32x32x16_bf16 v[16:31], v[140:143], v[236:239], v[16:31]
	ds_read_b64_tr_b16 v[236:237], v173 offset:5120
	ds_read_b64_tr_b16 v[238:239], v173 offset:7168
	v_exp_f32_e32 v189, v92
	v_exp_f32_e32 v191, v93
	v_exp_f32_e32 v188, v94
	s_waitcnt lgkmcnt(6)
	v_mfma_f32_32x32x16_bf16 v[16:31], v[208:211], v[240:243], v[16:31]
	ds_read_b64_tr_b16 v[240:241], v173 offset:9216
	ds_read_b64_tr_b16 v[242:243], v173 offset:11264
	v_exp_f32_e32 v190, v95
	v_mov_b32_e32 v168, v64
	v_mov_b32_e32 v169, v65
	s_waitcnt lgkmcnt(6)
	v_mfma_f32_32x32x16_bf16 v[16:31], v[228:231], v[204:207], v[16:31]
	ds_read_b64_tr_b16 v[204:205], v173 offset:13312
	ds_read_b64_tr_b16 v[206:207], v173 offset:15360
	v_mov_b32_e32 v166, v66
	v_mov_b32_e32 v167, v67
	v_mov_b32_e32 v164, v68
	s_waitcnt lgkmcnt(6)
	v_mfma_f32_32x32x16_bf16 v[32:47], v[136:139], v[232:235], v[32:47]
	ds_read_b64_tr_b16 v[232:233], v173 offset:1536
	ds_read_b64_tr_b16 v[234:235], v173 offset:3584
	v_mov_b32_e32 v165, v69
	v_mov_b32_e32 v150, v70
	v_mov_b32_e32 v151, v71
	s_waitcnt lgkmcnt(6)
	v_mfma_f32_32x32x16_bf16 v[32:47], v[140:143], v[236:239], v[32:47]
	ds_read_b64_tr_b16 v[236:237], v173 offset:5632
	ds_read_b64_tr_b16 v[238:239], v173 offset:7680
	v_mov_b32_e32 v162, v72
	v_mov_b32_e32 v163, v73
	v_mov_b32_e32 v148, v74
	s_waitcnt lgkmcnt(6)
	v_mfma_f32_32x32x16_bf16 v[32:47], v[208:211], v[240:243], v[32:47]
	ds_read_b64_tr_b16 v[240:241], v173 offset:9728
	ds_read_b64_tr_b16 v[242:243], v173 offset:11776
	v_mov_b32_e32 v149, v75
	v_mov_b32_e32 v146, v76
	v_mov_b32_e32 v147, v77
	s_waitcnt lgkmcnt(6)
	v_mfma_f32_32x32x16_bf16 v[32:47], v[228:231], v[204:207], v[32:47]
	ds_read_b64_tr_b16 v[204:205], v173 offset:13824
	ds_read_b64_tr_b16 v[206:207], v173 offset:15872
	v_mov_b32_e32 v144, v78
	v_mov_b32_e32 v145, v79
	s_waitcnt vmcnt(2) lgkmcnt(0)
	s_barrier
; #define SBAR() __builtin_amdgcn_sched_barrier(0)
; __device__ __forceinline__ void finishSM(f32x16& p0, f32x16& p1, float& l_reg, bf16x8& pa0, bf16x8& pa1, bf16x8& pa2, bf16x8& pa3) {
; #pragma unroll
;   for (int r = 0; r < 16; ++r) p1[r] = __builtin_amdgcn_exp2f(p1[r]);
;   float ps = 0;
; #pragma unroll
;   for (int r = 0; r < 16; ++r) ps += p0[r];
; #pragma unroll
;   for (int r = 0; r < 16; ++r) ps += p1[r];
;   l_reg += ps;
;     ...
;   PK4(p0, 0, pa0); PK4(p0, 8, pa1); PK4(p1, 0, pa2); PK4(p1, 8, pa3);
;     ...
; }
; __device__ __forceinline__ void qkt(f32x16& p0, f32x16& p1, const bf16* Ks, const bf16x8* qr, int r32, int hi) {
;   p0 = f32x16{}; p1 = f32x16{};
; #pragma unroll
;   for (int d0 = 0; d0 < 8; ++d0) { int cb = (d0 * 16 + hi * 8) * 2;
;     bf16x8 b0 = *reinterpret_cast<const bf16x8*>((const char*)Ks + KSWZ(r32, cb));
;     bf16x8 b1 = *reinterpret_cast<const bf16x8*>((const char*)Ks + KSWZ(32 + r32, cb));
;     p0 = __builtin_amdgcn_mfma_f32_32x32x16_bf16(b0, qr[d0], p0, 0, 0, 0);
;     p1 = __builtin_amdgcn_mfma_f32_32x32x16_bf16(b1, qr[d0], p1, 0, 0, 0); }
; }
; __device__ __forceinline__ int v_st(int k, int c) { const int kk = (k & ~0xC) | ((k & 4) << 1) | ((k & 8) >> 1); return ((kk >> 3) * 4 + (c >> 5)) * 512 + ((kk & 7) * 32 + (c & 31)) * 2; }
; __device__ __forceinline__ int v_rd_base(int lane) { return ((lane & 3) << 3) | (((lane >> 2) & 3) << 6) | (((lane >> 4) & 1) << 5) | (((lane >> 5) & 1) << 8); }
; template <int OFF> __device__ __forceinline__ s16x4 tr_read(int vb) {
;   s16x4 r; asm volatile("ds_read_b64_tr_b16 %0, %1 offset:%2" : "=&v"(r) : "v"(vb), "i"(OFF) : "memory"); return r;
; }
; template <int D0> __device__ __forceinline__ void pv_one(f32x16& od, int vb, bf16x8 pa0, bf16x8 pa1, bf16x8 pa2, bf16x8 pa3) {
;   const s16x4 l0 = tr_read<v_rd_off(D0, 0, 0)>(vb), h0 = tr_read<v_rd_off(D0, 0, 1)>(vb), l1 = tr_read<v_rd_off(D0, 1, 0)>(vb), h1 = tr_read<v_rd_off(D0, 1, 1)>(vb);
;   const s16x4 l2 = tr_read<v_rd_off(D0, 2, 0)>(vb), h2 = tr_read<v_rd_off(D0, 2, 1)>(vb), l3 = tr_read<v_rd_off(D0, 3, 0)>(vb), h3 = tr_read<v_rd_off(D0, 3, 1)>(vb);
;   asm volatile("s_waitcnt lgkmcnt(0)" ::: "memory"); SBAR();
;     ...
;   od = __builtin_amdgcn_mfma_f32_32x32x16_bf16(pa0, PK(l0, h0), od, 0, 0, 0);
;   od = __builtin_amdgcn_mfma_f32_32x32x16_bf16(pa1, PK(l1, h1), od, 0, 0, 0);
;   od = __builtin_amdgcn_mfma_f32_32x32x16_bf16(pa2, PK(l2, h2), od, 0, 0, 0);
	v_mfma_f32_32x32x16_bf16 v[48:63], v[136:139], v[232:235], v[48:63]
	v_mfma_f32_32x32x16_bf16 v[48:63], v[140:143], v[236:239], v[48:63]
	v_mfma_f32_32x32x16_bf16 v[48:63], v[208:211], v[240:243], v[48:63]
	v_mfma_f32_32x32x16_bf16 v[48:63], v[228:231], v[204:207], v[48:63]
	v_mov_b32_e32 v173, v153
	v_add_u32_e32 v153, 0x4000, v153
	v_and_b32_e32 v64, 0x3fffffc0, v174
	s_add_i32 s12, 0, 0x10000
	v_lshl_add_u32 v128, v64, 2, s12
	ds_read_b128 v[64:67], v179 offset:16384
	ds_read_b128 v[68:71], v179 offset:24576
	s_waitcnt lgkmcnt(1)
	v_mfma_f32_32x32x16_bf16 v[80:95], v[64:67], v[124:127], 0
	s_waitcnt lgkmcnt(0)
	v_mfma_f32_32x32x16_bf16 v[64:79], v[68:71], v[124:127], 0
	ds_read_b128 v[124:127], v182 offset:16384
	ds_read_b128 v[130:133], v182 offset:24576
	s_waitcnt lgkmcnt(1)
	v_mfma_f32_32x32x16_bf16 v[80:95], v[124:127], v[120:123], v[80:95]
	s_waitcnt lgkmcnt(0)
	v_mfma_f32_32x32x16_bf16 v[64:79], v[130:133], v[120:123], v[64:79]
	ds_read_b128 v[120:123], v183 offset:16384
	ds_read_b128 v[124:127], v183 offset:24576
	s_waitcnt lgkmcnt(1)
	v_mfma_f32_32x32x16_bf16 v[80:95], v[120:123], v[116:119], v[80:95]
	s_waitcnt lgkmcnt(0)
	v_mfma_f32_32x32x16_bf16 v[64:79], v[124:127], v[116:119], v[64:79]
	ds_read_b128 v[116:119], v184 offset:16384
	ds_read_b128 v[120:123], v184 offset:24576
	s_waitcnt lgkmcnt(1)
	v_mfma_f32_32x32x16_bf16 v[80:95], v[116:119], v[112:115], v[80:95]
	s_waitcnt lgkmcnt(0)
	v_mfma_f32_32x32x16_bf16 v[64:79], v[120:123], v[112:115], v[64:79]
	ds_read_b128 v[112:115], v185 offset:16384
	ds_read_b128 v[116:119], v185 offset:24576
	s_waitcnt lgkmcnt(1)
	v_mfma_f32_32x32x16_bf16 v[80:95], v[112:115], v[108:111], v[80:95]
	s_waitcnt lgkmcnt(0)
	v_mfma_f32_32x32x16_bf16 v[64:79], v[116:119], v[108:111], v[64:79]
	ds_read_b128 v[108:111], v186 offset:16384
	ds_read_b128 v[112:115], v186 offset:24576
	v_exp_f32_e32 v116, v146
	v_exp_f32_e32 v117, v147
	v_exp_f32_e32 v118, v144
	v_exp_f32_e32 v119, v145
	s_waitcnt lgkmcnt(1)
	v_mfma_f32_32x32x16_bf16 v[80:95], v[108:111], v[104:107], v[80:95]
	s_waitcnt lgkmcnt(0)
	v_mfma_f32_32x32x16_bf16 v[64:79], v[112:115], v[104:107], v[64:79]
	ds_read_b128 v[104:107], v180 offset:16384
	ds_read_b128 v[108:111], v180 offset:24576
	v_exp_f32_e32 v112, v162
	v_exp_f32_e32 v113, v163
	v_exp_f32_e32 v114, v148
	v_exp_f32_e32 v115, v149
	s_waitcnt lgkmcnt(1)
	v_mfma_f32_32x32x16_bf16 v[80:95], v[104:107], v[100:103], v[80:95]
	s_waitcnt lgkmcnt(0)
	v_mfma_f32_32x32x16_bf16 v[64:79], v[108:111], v[100:103], v[64:79]
	ds_read_b128 v[100:103], v181 offset:16384
	ds_read_b128 v[104:107], v181 offset:24576
	v_exp_f32_e32 v108, v164
	v_exp_f32_e32 v109, v165
	v_exp_f32_e32 v110, v150
	v_exp_f32_e32 v111, v151
	s_waitcnt lgkmcnt(1)
	v_mfma_f32_32x32x16_bf16 v[80:95], v[100:103], v[96:99], v[80:95]
	s_waitcnt lgkmcnt(0)
	v_mfma_f32_32x32x16_bf16 v[64:79], v[104:107], v[96:99], v[64:79]
	v_add_f32_e32 v96, 0, v199
	v_add_f32_e32 v96, v201, v96
	v_add_f32_e32 v96, v198, v96
	v_add_f32_e32 v96, v203, v96
	v_add_f32_e32 v96, v200, v96
	v_add_f32_e32 v96, v202, v96
	v_add_f32_e32 v96, v196, v96
	v_add_f32_e32 v96, v197, v96
	v_add_f32_e32 v96, v193, v96
	v_add_f32_e32 v96, v195, v96
	v_add_f32_e32 v96, v192, v96
	v_add_f32_e32 v96, v194, v96
	v_exp_f32_e32 v104, v168
	v_add_f32_e32 v96, v189, v96
	v_exp_f32_e32 v105, v169
	v_add_f32_e32 v96, v191, v96
	v_exp_f32_e32 v106, v166
	v_add_f32_e32 v96, v188, v96
	v_exp_f32_e32 v107, v167
	v_add_f32_e32 v96, v190, v96
	v_add_f32_e32 v96, v104, v96
	v_add_f32_e32 v96, v105, v96
	v_add_f32_e32 v96, v106, v96
	v_add_f32_e32 v96, v107, v96
	v_add_f32_e32 v96, v108, v96
	v_add_f32_e32 v96, v109, v96
	v_add_f32_e32 v96, v110, v96
	v_add_f32_e32 v96, v111, v96
	v_add_f32_e32 v96, v112, v96
	v_add_f32_e32 v96, v113, v96
	v_add_f32_e32 v96, v114, v96
	v_add_f32_e32 v96, v115, v96
	v_add_f32_e32 v96, v116, v96
	v_add_f32_e32 v96, v117, v96
	v_add_f32_e32 v96, v118, v96
	v_add_f32_e32 v96, v119, v96
	v_add_f32_e32 v129, v187, v96
	v_cvt_pk_bf16_f32 v96, v199, v201
	v_cvt_pk_bf16_f32 v97, v198, v203
	v_cvt_pk_bf16_f32 v98, v200, v202
	v_cvt_pk_bf16_f32 v99, v196, v197
	v_cvt_pk_bf16_f32 v100, v193, v195
	v_cvt_pk_bf16_f32 v101, v192, v194
	v_cvt_pk_bf16_f32 v102, v189, v191
	v_cvt_pk_bf16_f32 v103, v188, v190
	v_cvt_pk_bf16_f32 v104, v104, v105
	v_cvt_pk_bf16_f32 v105, v106, v107
	v_cvt_pk_bf16_f32 v106, v108, v109
	v_cvt_pk_bf16_f32 v107, v110, v111
	v_cvt_pk_bf16_f32 v108, v112, v113
	v_cvt_pk_bf16_f32 v109, v114, v115
	v_cvt_pk_bf16_f32 v110, v116, v117
	v_cvt_pk_bf16_f32 v111, v118, v119
	s_nop 0
	v_permlane32_swap_b32_e32 v96, v98
	v_permlane32_swap_b32_e32 v97, v99
	v_permlane32_swap_b32_e32 v100, v102
	v_permlane32_swap_b32_e32 v101, v103
	v_permlane32_swap_b32_e32 v104, v106
	v_permlane32_swap_b32_e32 v105, v107
	v_permlane32_swap_b32_e32 v108, v110
	v_permlane32_swap_b32_e32 v109, v111
	ds_read_b64_tr_b16 v[112:113], v173 offset:0
	ds_read_b64_tr_b16 v[114:115], v173 offset:0x800
	ds_read_b64_tr_b16 v[116:117], v173 offset:0x1000
	ds_read_b64_tr_b16 v[118:119], v173 offset:0x1800
	ds_read_b64_tr_b16 v[120:121], v173 offset:0x2000
	ds_read_b64_tr_b16 v[122:123], v173 offset:0x2800
	ds_read_b64_tr_b16 v[124:125], v173 offset:0x3000
	ds_read_b64_tr_b16 v[126:127], v173 offset:0x3800
	s_waitcnt lgkmcnt(0)
	s_nop 0
	v_mfma_f32_32x32x16_bf16 v[0:15], v[96:99], v[112:115], v[0:15]
	ds_read_b64_tr_b16 v[112:113], v173 offset:0x200
	ds_read_b64_tr_b16 v[114:115], v173 offset:0xa00
	v_mfma_f32_32x32x16_bf16 v[0:15], v[100:103], v[116:119], v[0:15]
	ds_read_b64_tr_b16 v[116:117], v173 offset:0x1200
	ds_read_b64_tr_b16 v[118:119], v173 offset:0x1a00
	v_mfma_f32_32x32x16_bf16 v[0:15], v[104:107], v[120:123], v[0:15]
	ds_read_b64_tr_b16 v[120:121], v173 offset:0x2200
	ds_read_b64_tr_b16 v[122:123], v173 offset:0x2a00
	v_mfma_f32_32x32x16_bf16 v[0:15], v[108:111], v[124:127], v[0:15]
	ds_read_b64_tr_b16 v[124:125], v173 offset:0x3200
	ds_read_b64_tr_b16 v[126:127], v173 offset:0x3a00
	s_waitcnt lgkmcnt(0)
; __device__ __forceinline__ void partialSM(f32x16& p0, f32x16& p1, float mnC) {
;   constexpr float C = SCALE * 1.4426950408889634f;
; #pragma unroll
;   for (int r = 0; r < 16; ++r) p0[r] = fmaf(p0[r], C, mnC);
; #pragma unroll
;   for (int r = 0; r < 16; ++r) p1[r] = fmaf(p1[r], C, mnC);
; #pragma unroll
;   for (int r = 0; r < 16; ++r) p0[r] = __builtin_amdgcn_exp2f(p0[r]);
; }
; __device__ __forceinline__ void finishSM(f32x16& p0, f32x16& p1, float& l_reg, bf16x8& pa0, bf16x8& pa1, bf16x8& pa2, bf16x8& pa3) {
; #pragma unroll
;   for (int r = 0; r < 16; ++r) p1[r] = __builtin_amdgcn_exp2f(p1[r]);
;   float ps = 0;
; #pragma unroll
;   for (int r = 0; r < 16; ++r) ps += p0[r];
; #pragma unroll
;   for (int r = 0; r < 16; ++r) ps += p1[r];
;   l_reg += ps;
;     ...
;   PK4(p0, 0, pa0); PK4(p0, 8, pa1); PK4(p1, 0, pa2); PK4(p1, 8, pa3);
;     ...
; }
; __device__ __forceinline__ void qkt(f32x16& p0, f32x16& p1, const bf16* Ks, const bf16x8* qr, int r32, int hi) {
;   p0 = f32x16{}; p1 = f32x16{};
; #pragma unroll
;   for (int d0 = 0; d0 < 8; ++d0) { int cb = (d0 * 16 + hi * 8) * 2;
;     bf16x8 b0 = *reinterpret_cast<const bf16x8*>((const char*)Ks + KSWZ(r32, cb));
;     bf16x8 b1 = *reinterpret_cast<const bf16x8*>((const char*)Ks + KSWZ(32 + r32, cb));
;     p0 = __builtin_amdgcn_mfma_f32_32x32x16_bf16(b0, qr[d0], p0, 0, 0, 0);
;     p1 = __builtin_amdgcn_mfma_f32_32x32x16_bf16(b1, qr[d0], p1, 0, 0, 0); }
; }
; __device__ __forceinline__ int v_st(int k, int c) { const int kk = (k & ~0xC) | ((k & 4) << 1) | ((k & 8) >> 1); return ((kk >> 3) * 4 + (c >> 5)) * 512 + ((kk & 7) * 32 + (c & 31)) * 2; }
; __device__ __forceinline__ int v_rd_base(int lane) { return ((lane & 3) << 3) | (((lane >> 2) & 3) << 6) | (((lane >> 4) & 1) << 5) | (((lane >> 5) & 1) << 8); }
; template <int OFF> __device__ __forceinline__ s16x4 tr_read(int vb) {
;   s16x4 r; asm volatile("ds_read_b64_tr_b16 %0, %1 offset:%2" : "=&v"(r) : "v"(vb), "i"(OFF) : "memory"); return r;
; }
; template <int D0> __device__ __forceinline__ void pv_one(f32x16& od, int vb, bf16x8 pa0, bf16x8 pa1, bf16x8 pa2, bf16x8 pa3) {
;   const s16x4 l0 = tr_read<v_rd_off(D0, 0, 0)>(vb), h0 = tr_read<v_rd_off(D0, 0, 1)>(vb), l1 = tr_read<v_rd_off(D0, 1, 0)>(vb), h1 = tr_read<v_rd_off(D0, 1, 1)>(vb);
	v_mfma_f32_32x32x16_bf16 v[16:31], v[96:99], v[112:115], v[16:31]
	ds_read_b64_tr_b16 v[112:113], v173 offset:0x400
	ds_read_b64_tr_b16 v[114:115], v173 offset:0xc00
	v_mfma_f32_32x32x16_bf16 v[16:31], v[100:103], v[116:119], v[16:31]
	ds_read_b64_tr_b16 v[116:117], v173 offset:0x1400
	ds_read_b64_tr_b16 v[118:119], v173 offset:0x1c00
	v_mfma_f32_32x32x16_bf16 v[16:31], v[104:107], v[120:123], v[16:31]
	ds_read_b64_tr_b16 v[120:121], v173 offset:0x2400
	ds_read_b64_tr_b16 v[122:123], v173 offset:0x2c00
	v_mfma_f32_32x32x16_bf16 v[16:31], v[108:111], v[124:127], v[16:31]
	ds_read_b64_tr_b16 v[124:125], v173 offset:0x3400
	ds_read_b64_tr_b16 v[126:127], v173 offset:0x3c00
	s_waitcnt lgkmcnt(0)
	v_mfma_f32_32x32x16_bf16 v[32:47], v[96:99], v[112:115], v[32:47]
	ds_read_b64_tr_b16 v[112:113], v173 offset:0x600
	ds_read_b64_tr_b16 v[114:115], v173 offset:0xe00
	v_mfma_f32_32x32x16_bf16 v[32:47], v[100:103], v[116:119], v[32:47]
	ds_read_b64_tr_b16 v[116:117], v173 offset:0x1600
	ds_read_b64_tr_b16 v[118:119], v173 offset:0x1e00
	v_mfma_f32_32x32x16_bf16 v[32:47], v[104:107], v[120:123], v[32:47]
	ds_read_b64_tr_b16 v[120:121], v173 offset:0x2600
	ds_read_b64_tr_b16 v[122:123], v173 offset:0x2e00
	v_mfma_f32_32x32x16_bf16 v[32:47], v[108:111], v[124:127], v[32:47]
	ds_read_b64_tr_b16 v[124:125], v173 offset:0x3600
	ds_read_b64_tr_b16 v[126:127], v173 offset:0x3e00
	s_waitcnt lgkmcnt(0)
	v_fmamk_f32 v80, v80, 0x3f800000, v152
	v_fmamk_f32 v81, v81, 0x3f800000, v152
	v_exp_f32_e32 v80, v80
	v_fmamk_f32 v82, v82, 0x3f800000, v152
	v_exp_f32_e32 v81, v81
	v_fmamk_f32 v83, v83, 0x3f800000, v152
	v_exp_f32_e32 v82, v82
	v_fmamk_f32 v84, v84, 0x3f800000, v152
	v_fmamk_f32 v64, v64, 0x3f800000, v152
	v_exp_f32_e32 v83, v83
	v_mfma_f32_32x32x16_bf16 v[48:63], v[96:99], v[112:115], v[48:63]
	v_fmamk_f32 v85, v85, 0x3f800000, v152
	v_exp_f32_e32 v84, v84
	v_exp_f32_e32 v96, v64
	v_add_f32_e32 v64, 0, v80
	v_fmamk_f32 v86, v86, 0x3f800000, v152
	v_exp_f32_e32 v85, v85
	v_add_f32_e32 v64, v81, v64
	v_fmamk_f32 v87, v87, 0x3f800000, v152
	v_exp_f32_e32 v86, v86
	v_add_f32_e32 v64, v82, v64
	v_fmamk_f32 v88, v88, 0x3f800000, v152
	v_exp_f32_e32 v87, v87
	v_add_f32_e32 v64, v83, v64
	v_fmamk_f32 v89, v89, 0x3f800000, v152
	v_exp_f32_e32 v88, v88
	v_add_f32_e32 v64, v84, v64
	v_fmamk_f32 v90, v90, 0x3f800000, v152
	v_exp_f32_e32 v89, v89
	v_add_f32_e32 v64, v85, v64
	v_fmamk_f32 v91, v91, 0x3f800000, v152
	v_exp_f32_e32 v90, v90
	v_add_f32_e32 v64, v86, v64
	v_fmamk_f32 v92, v92, 0x3f800000, v152
	v_exp_f32_e32 v91, v91
	v_add_f32_e32 v64, v87, v64
	v_fmamk_f32 v93, v93, 0x3f800000, v152
	v_exp_f32_e32 v92, v92
	v_add_f32_e32 v64, v88, v64
	v_mfma_f32_32x32x16_bf16 v[48:63], v[100:103], v[116:119], v[48:63]
	v_fmamk_f32 v94, v94, 0x3f800000, v152
	v_exp_f32_e32 v93, v93
	v_add_f32_e32 v64, v89, v64
	v_fmamk_f32 v95, v95, 0x3f800000, v152
	v_exp_f32_e32 v94, v94
	v_add_f32_e32 v64, v90, v64
	v_exp_f32_e32 v95, v95
	v_add_f32_e32 v64, v91, v64
	v_fmamk_f32 v65, v65, 0x3f800000, v152
	v_add_f32_e32 v64, v92, v64
	v_fmamk_f32 v66, v66, 0x3f800000, v152
	v_exp_f32_e32 v65, v65
	v_add_f32_e32 v64, v93, v64
	v_fmamk_f32 v67, v67, 0x3f800000, v152
	v_exp_f32_e32 v97, v66
	v_add_f32_e32 v64, v94, v64
	v_fmamk_f32 v68, v68, 0x3f800000, v152
	v_exp_f32_e32 v98, v67
	v_add_f32_e32 v64, v95, v64
	v_fmamk_f32 v69, v69, 0x3f800000, v152
	v_exp_f32_e32 v99, v68
	v_add_f32_e32 v64, v96, v64
	v_mfma_f32_32x32x16_bf16 v[48:63], v[104:107], v[120:123], v[48:63]
	v_fmamk_f32 v70, v70, 0x3f800000, v152
	v_exp_f32_e32 v100, v69
	v_add_f32_e32 v64, v65, v64
	v_fmamk_f32 v71, v71, 0x3f800000, v152
	v_exp_f32_e32 v101, v70
	v_add_f32_e32 v64, v97, v64
	v_fmamk_f32 v72, v72, 0x3f800000, v152
	v_exp_f32_e32 v102, v71
	v_add_f32_e32 v64, v98, v64
	v_fmamk_f32 v73, v73, 0x3f800000, v152
	v_exp_f32_e32 v103, v72
	v_add_f32_e32 v64, v99, v64
	v_fmamk_f32 v74, v74, 0x3f800000, v152
	v_exp_f32_e32 v104, v73
	v_add_f32_e32 v64, v100, v64
	v_fmamk_f32 v75, v75, 0x3f800000, v152
	v_exp_f32_e32 v105, v74
	v_add_f32_e32 v64, v101, v64
	v_fmamk_f32 v76, v76, 0x3f800000, v152
	v_exp_f32_e32 v106, v75
	v_add_f32_e32 v64, v102, v64
	v_fmamk_f32 v77, v77, 0x3f800000, v152
	v_exp_f32_e32 v107, v76
	v_add_f32_e32 v64, v103, v64
	v_mfma_f32_32x32x16_bf16 v[48:63], v[108:111], v[124:127], v[48:63]
	v_fmamk_f32 v78, v78, 0x3f800000, v152
	v_exp_f32_e32 v108, v77
	v_add_f32_e32 v64, v104, v64
	v_fmamk_f32 v79, v79, 0x3f800000, v152
	v_exp_f32_e32 v109, v78
	v_add_f32_e32 v64, v105, v64
	v_exp_f32_e32 v110, v79
	v_add_f32_e32 v64, v106, v64
	v_add_f32_e32 v64, v107, v64
	v_add_f32_e32 v64, v108, v64
	v_add_f32_e32 v64, v109, v64
	v_add_f32_e32 v64, v110, v64
	s_waitcnt vmcnt(0)
	s_barrier
; #define SBAR() __builtin_amdgcn_sched_barrier(0)
; __device__ __forceinline__ void finishSM(f32x16& p0, f32x16& p1, float& l_reg, bf16x8& pa0, bf16x8& pa1, bf16x8& pa2, bf16x8& pa3) {
; #pragma unroll
;   for (int r = 0; r < 16; ++r) p1[r] = __builtin_amdgcn_exp2f(p1[r]);
;   float ps = 0;
; #pragma unroll
;   for (int r = 0; r < 16; ++r) ps += p0[r];
; #pragma unroll
;   for (int r = 0; r < 16; ++r) ps += p1[r];
;   l_reg += ps;
;     ...
;   PK4(p0, 0, pa0); PK4(p0, 8, pa1); PK4(p1, 0, pa2); PK4(p1, 8, pa3);
;     ...
; }
; __device__ __forceinline__ void qkt(f32x16& p0, f32x16& p1, const bf16* Ks, const bf16x8* qr, int r32, int hi) {
;   p0 = f32x16{}; p1 = f32x16{};
; #pragma unroll
;   for (int d0 = 0; d0 < 8; ++d0) { int cb = (d0 * 16 + hi * 8) * 2;
;     bf16x8 b0 = *reinterpret_cast<const bf16x8*>((const char*)Ks + KSWZ(r32, cb));
;     bf16x8 b1 = *reinterpret_cast<const bf16x8*>((const char*)Ks + KSWZ(32 + r32, cb));
;     p0 = __builtin_amdgcn_mfma_f32_32x32x16_bf16(b0, qr[d0], p0, 0, 0, 0);
;     p1 = __builtin_amdgcn_mfma_f32_32x32x16_bf16(b1, qr[d0], p1, 0, 0, 0); }
; }
; __device__ __forceinline__ int v_st(int k, int c) { const int kk = (k & ~0xC) | ((k & 4) << 1) | ((k & 8) >> 1); return ((kk >> 3) * 4 + (c >> 5)) * 512 + ((kk & 7) * 32 + (c & 31)) * 2; }
; __device__ __forceinline__ int v_rd_base(int lane) { return ((lane & 3) << 3) | (((lane >> 2) & 3) << 6) | (((lane >> 4) & 1) << 5) | (((lane >> 5) & 1) << 8); }
; template <int OFF> __device__ __forceinline__ s16x4 tr_read(int vb) {
;   s16x4 r; asm volatile("ds_read_b64_tr_b16 %0, %1 offset:%2" : "=&v"(r) : "v"(vb), "i"(OFF) : "memory"); return r;
; }
; template <int D0> __device__ __forceinline__ void pv_one(f32x16& od, int vb, bf16x8 pa0, bf16x8 pa1, bf16x8 pa2, bf16x8 pa3) {
;   const s16x4 l0 = tr_read<v_rd_off(D0, 0, 0)>(vb), h0 = tr_read<v_rd_off(D0, 0, 1)>(vb), l1 = tr_read<v_rd_off(D0, 1, 0)>(vb), h1 = tr_read<v_rd_off(D0, 1, 1)>(vb);
;   const s16x4 l2 = tr_read<v_rd_off(D0, 2, 0)>(vb), h2 = tr_read<v_rd_off(D0, 2, 1)>(vb), l3 = tr_read<v_rd_off(D0, 3, 0)>(vb), h3 = tr_read<v_rd_off(D0, 3, 1)>(vb);
;   asm volatile("s_waitcnt lgkmcnt(0)" ::: "memory"); SBAR();
;     ...
;   od = __builtin_amdgcn_mfma_f32_32x32x16_bf16(pa0, PK(l0, h0), od, 0, 0, 0);
;   od = __builtin_amdgcn_mfma_f32_32x32x16_bf16(pa1, PK(l1, h1), od, 0, 0, 0);
;   od = __builtin_amdgcn_mfma_f32_32x32x16_bf16(pa2, PK(l2, h2), od, 0, 0, 0);
	v_add_f32_e32 v64, v129, v64
	v_cvt_pk_bf16_f32 v66, v80, v81
	v_cvt_pk_bf16_f32 v67, v82, v83
	v_cvt_pk_bf16_f32 v68, v84, v85
	v_cvt_pk_bf16_f32 v69, v86, v87
	v_cvt_pk_bf16_f32 v70, v88, v89
	v_cvt_pk_bf16_f32 v71, v90, v91
	v_cvt_pk_bf16_f32 v72, v92, v93
	v_cvt_pk_bf16_f32 v73, v94, v95
	v_cvt_pk_bf16_f32 v74, v96, v65
	v_cvt_pk_bf16_f32 v75, v97, v98
	v_cvt_pk_bf16_f32 v76, v99, v100
	v_cvt_pk_bf16_f32 v77, v101, v102
	v_cvt_pk_bf16_f32 v78, v103, v104
	v_cvt_pk_bf16_f32 v79, v105, v106
	v_cvt_pk_bf16_f32 v80, v107, v108
	v_cvt_pk_bf16_f32 v81, v109, v110
	s_nop 0
	v_permlane32_swap_b32_e32 v66, v68
	v_permlane32_swap_b32_e32 v67, v69
	v_permlane32_swap_b32_e32 v70, v72
	v_permlane32_swap_b32_e32 v71, v73
	v_permlane32_swap_b32_e32 v74, v76
	v_permlane32_swap_b32_e32 v75, v77
	v_permlane32_swap_b32_e32 v78, v80
	v_permlane32_swap_b32_e32 v79, v81
	ds_read_b64_tr_b16 v[82:83], v153 offset:0
	ds_read_b64_tr_b16 v[84:85], v153 offset:0x800
	ds_read_b64_tr_b16 v[86:87], v153 offset:0x1000
	ds_read_b64_tr_b16 v[88:89], v153 offset:0x1800
	ds_read_b64_tr_b16 v[90:91], v153 offset:0x2000
	ds_read_b64_tr_b16 v[92:93], v153 offset:0x2800
	ds_read_b64_tr_b16 v[94:95], v153 offset:0x3000
	ds_read_b64_tr_b16 v[96:97], v153 offset:0x3800
	s_waitcnt lgkmcnt(0)
	s_nop 0
	v_mfma_f32_32x32x16_bf16 v[0:15], v[66:69], v[82:85], v[0:15]
	ds_read_b64_tr_b16 v[82:83], v153 offset:0x200
	ds_read_b64_tr_b16 v[84:85], v153 offset:0xa00
	v_mfma_f32_32x32x16_bf16 v[0:15], v[70:73], v[86:89], v[0:15]
	ds_read_b64_tr_b16 v[86:87], v153 offset:0x1200
	ds_read_b64_tr_b16 v[88:89], v153 offset:0x1a00
	v_mfma_f32_32x32x16_bf16 v[0:15], v[74:77], v[90:93], v[0:15]
	ds_read_b64_tr_b16 v[90:91], v153 offset:0x2200
	ds_read_b64_tr_b16 v[92:93], v153 offset:0x2a00
	v_mfma_f32_32x32x16_bf16 v[0:15], v[78:81], v[94:97], v[0:15]
	ds_read_b64_tr_b16 v[94:95], v153 offset:0x3200
	ds_read_b64_tr_b16 v[96:97], v153 offset:0x3a00
	s_waitcnt lgkmcnt(0)
	v_mfma_f32_32x32x16_bf16 v[16:31], v[66:69], v[82:85], v[16:31]
	ds_read_b64_tr_b16 v[82:83], v153 offset:0x400
	ds_read_b64_tr_b16 v[84:85], v153 offset:0xc00
	v_mfma_f32_32x32x16_bf16 v[16:31], v[70:73], v[86:89], v[16:31]
	ds_read_b64_tr_b16 v[86:87], v153 offset:0x1400
	ds_read_b64_tr_b16 v[88:89], v153 offset:0x1c00
	v_mfma_f32_32x32x16_bf16 v[16:31], v[74:77], v[90:93], v[16:31]
	ds_read_b64_tr_b16 v[90:91], v153 offset:0x2400
	ds_read_b64_tr_b16 v[92:93], v153 offset:0x2c00
	v_mfma_f32_32x32x16_bf16 v[16:31], v[78:81], v[94:97], v[16:31]
	ds_read_b64_tr_b16 v[94:95], v153 offset:0x3400
	ds_read_b64_tr_b16 v[96:97], v153 offset:0x3c00
	s_waitcnt lgkmcnt(0)
	v_mfma_f32_32x32x16_bf16 v[32:47], v[66:69], v[82:85], v[32:47]
	ds_read_b64_tr_b16 v[82:83], v153 offset:0x600
	ds_read_b64_tr_b16 v[84:85], v153 offset:0xe00
	v_mfma_f32_32x32x16_bf16 v[32:47], v[70:73], v[86:89], v[32:47]
	ds_read_b64_tr_b16 v[86:87], v153 offset:0x1600
	ds_read_b64_tr_b16 v[88:89], v153 offset:0x1e00
	v_mfma_f32_32x32x16_bf16 v[32:47], v[74:77], v[90:93], v[32:47]
	ds_read_b64_tr_b16 v[90:91], v153 offset:0x2600
	ds_read_b64_tr_b16 v[92:93], v153 offset:0x2e00
	v_mfma_f32_32x32x16_bf16 v[32:47], v[78:81], v[94:97], v[32:47]
	ds_read_b64_tr_b16 v[94:95], v153 offset:0x3600
	ds_read_b64_tr_b16 v[96:97], v153 offset:0x3e00
	s_waitcnt lgkmcnt(0)
	v_mfma_f32_32x32x16_bf16 v[48:63], v[66:69], v[82:85], v[48:63]
	v_mov_b32_e32 v65, v64
	s_nop 1
	v_permlane32_swap_b32_e32 v64, v65
	v_mfma_f32_32x32x16_bf16 v[48:63], v[70:73], v[86:89], v[48:63]
	v_mfma_f32_32x32x16_bf16 v[48:63], v[74:77], v[90:93], v[48:63]
	v_mfma_f32_32x32x16_bf16 v[48:63], v[78:81], v[94:97], v[48:63]
	s_setprio 0
	v_cmp_gt_u32_e32 vcc, 32, v159
	s_and_saveexec_b64 s[12:13], vcc
	s_cbranch_execz .LBB0_1036
	v_add_f32_e32 v64, v64, v65
	v_lshl_add_u32 v65, v171, 2, v128
	ds_write_b32 v65, v64
	s_branch .LBB0_1036
